# v13 plus: one B-fragment base VGPR per unit (v249) with immediate ds_read offsets: the six v_add_u32 per K-loop trip (two of them inside MFMA groups) are gone, no VALU besides MFMA in the K-loop
# speedup vs baseline: 1.0125x; 1.0060x over previous
; #define PG8_STAGE(bufoff, gbase, voff) do { _Pragma("unroll") for (int _i = 0; _i < 2; ++_i) \
;         __builtin_amdgcn_global_load_lds((const unsigned*)((const char*)(gbase) + (voff)[_i]), (LAS unsigned*)(lds + (bufoff) + ldsw + _i * 8192), 16, 0, 0); } while (0)
; #define PG8_LDA(dst, b, h) do { _Pragma("unroll") for (int m = 0; m < 4; ++m) _Pragma("unroll") for (int k = 0; k < 2; ++k) dst[m][k] = *(const LAS bf16x8*)(lds + PG8_SA(b, h) + aoff + m * 2048 + k * 1024); } while (0)
; #define PG8_LDB(dst, b, h) do { _Pragma("unroll") for (int n = 0; n < 2; ++n) _Pragma("unroll") for (int k = 0; k < 2; ++k) dst[n][k] = *(const LAS bf16x8*)(lds + PG8_SB(b, h) + boff + n * 2048 + k * 1024); } while (0)
; #define PG8_MMA(ai, bj, At, Bt) do { __builtin_amdgcn_s_setprio(1); _Pragma("unroll") for (int m = 0; m < 4; ++m) _Pragma("unroll") for (int n = 0; n < 2; ++n) _Pragma("unroll") for (int k = 0; k < 2; ++k) \
;         acc[ai][bj][m][n] = __builtin_amdgcn_mfma_f32_16x16x32_bf16(Bt[n][k], At[m][k], acc[ai][bj][m][n], 0, 0, 0); __builtin_amdgcn_s_setprio(0); } while (0)
; #define PG8_WAIT_V(n) asm volatile("s_waitcnt vmcnt(" #n ")" ::: "memory")
; #define PG8_WAIT_L(n) asm volatile("s_waitcnt lgkmcnt(" #n ")" ::: "memory")
; #define PG8_BAR __builtin_amdgcn_s_barrier()
; template <class Epi, class Sched>
; __device__ __forceinline__ void gemm_phase(LAS unsigned char* lds, const Gemm g, const Sched& S, const Epi& E) {
;     ...
;             const bool last = (t == nt - 2);
;             const char* a1 = cA + (size_t)(t + 1) * kstep;
;             const char* a2 = last ? nA : cA + (size_t)(t + 2) * kstep; const char* b2 = last ? nB : cB + (size_t)(t + 2) * kstep;
;             const char* a3 = a2 + kstep; const char* b3 = b2 + kstep;
;             PG8_LDB(B0, 0, 0); PG8_SCHED; PG8_LDA(At, 0, 0); PG8_STAGE(PG8_SA(1, 1), a1 + hstep, voffA);
;             PG8_WAIT_L(8); PG8_BAR; PG8_WAIT_L(0); PG8_MMA(0, 0, At, B0); PG8_BAR; PG8_SCHED;
;             PG8_LDB(B1, 0, 1); PG8_STAGE(PG8_SB(0, 0), b2, voffB);
;             PG8_BAR; PG8_WAIT_L(0); PG8_MMA(0, 1, At, B1); PG8_BAR;
;             PG8_LDA(At, 0, 1); PG8_STAGE(PG8_SA(0, 0), a2, voffA);
;             PG8_BAR; PG8_WAIT_L(0); PG8_MMA(1, 0, At, B0); PG8_BAR; PG8_SCHED;
;             PG8_STAGE(PG8_SB(0, 1), b2 + hstep, voffB);
;             PG8_WAIT_V(6); PG8_BAR; PG8_MMA(1, 1, At, B1); PG8_BAR;
.LBB0_165:
	s_add_u32 s24, s38, 0xfffc0080
	s_addc_u32 s25, s39, -1
	s_add_i32 vcc_hi, 0, 0x10000
	s_cmp_eq_u32 s50, 12
	s_cselect_b32 s61, s34, s25
	s_cselect_b32 s60, s45, s24
	s_cselect_b32 s49, s43, s35
	s_cselect_b32 s48, s79, vcc_lo
	s_add_i32 m0, s93, 0xc000
	ds_read_b128 v[214:217], v169 offset:6144
	ds_read_b128 v[218:221], v169 offset:7168
	global_load_lds_dwordx4 v140, s[38:39]
	s_add_i32 m0, s93, 0xe000
	s_nop 0
	global_load_lds_dwordx4 v138, s[38:39]
	s_waitcnt lgkmcnt(8)
	s_barrier
	s_waitcnt lgkmcnt(0)
	s_setprio 1
	s_waitcnt lgkmcnt(0)
	v_mfma_f32_16x16x32_bf16 v[126:129], v[142:145], v[190:193], v[126:129]
	v_mfma_f32_16x16x32_bf16 v[126:129], v[162:165], v[194:197], v[126:129]
	v_mfma_f32_16x16x32_bf16 v[122:125], v[182:185], v[190:193], v[122:125]
	v_mfma_f32_16x16x32_bf16 v[122:125], v[186:189], v[194:197], v[122:125]
	v_mfma_f32_16x16x32_bf16 v[110:113], v[142:145], v[198:201], v[110:113]
	v_mfma_f32_16x16x32_bf16 v[110:113], v[162:165], v[202:205], v[110:113]
	v_mfma_f32_16x16x32_bf16 v[106:109], v[182:185], v[198:201], v[106:109]
	v_mfma_f32_16x16x32_bf16 v[106:109], v[186:189], v[202:205], v[106:109]
	v_mfma_f32_16x16x32_bf16 v[94:97], v[142:145], v[206:209], v[94:97]
	v_mfma_f32_16x16x32_bf16 v[94:97], v[162:165], v[210:213], v[94:97]
	v_mfma_f32_16x16x32_bf16 v[90:93], v[182:185], v[206:209], v[90:93]
	v_mfma_f32_16x16x32_bf16 v[90:93], v[186:189], v[210:213], v[90:93]
	v_mfma_f32_16x16x32_bf16 v[78:81], v[142:145], v[214:217], v[78:81]
	v_mfma_f32_16x16x32_bf16 v[78:81], v[162:165], v[218:221], v[78:81]
	v_mfma_f32_16x16x32_bf16 v[74:77], v[182:185], v[214:217], v[74:77]
	s_barrier
	v_mfma_f32_16x16x32_bf16 v[74:77], v[186:189], v[218:221], v[74:77]
	s_setprio 0
	s_add_i32 s51, 0, 0x14000
	s_add_i32 s24, vcc_hi, s86
	s_mov_b32 m0, s24
	ds_read_b128 v[222:225], v249 offset:16384
	ds_read_b128 v[226:229], v249 offset:17408
	ds_read_b128 v[230:233], v249 offset:18432
	ds_read_b128 v[234:237], v249 offset:19456
	global_load_lds_dwordx4 v134, s[48:49]
	s_add_i32 m0, s24, 0x2000
	s_nop 0
	global_load_lds_dwordx4 v130, s[48:49]
	s_barrier
	s_waitcnt lgkmcnt(0)
	s_setprio 1
	s_waitcnt lgkmcnt(0)
	v_mfma_f32_16x16x32_bf16 v[118:121], v[222:225], v[190:193], v[118:121]
	v_mfma_f32_16x16x32_bf16 v[118:121], v[226:229], v[194:197], v[118:121]
	v_mfma_f32_16x16x32_bf16 v[114:117], v[230:233], v[190:193], v[114:117]
	v_mfma_f32_16x16x32_bf16 v[114:117], v[234:237], v[194:197], v[114:117]
	v_mfma_f32_16x16x32_bf16 v[102:105], v[222:225], v[198:201], v[102:105]
	v_mfma_f32_16x16x32_bf16 v[102:105], v[226:229], v[202:205], v[102:105]
	v_mfma_f32_16x16x32_bf16 v[98:101], v[230:233], v[198:201], v[98:101]
	v_mfma_f32_16x16x32_bf16 v[98:101], v[234:237], v[202:205], v[98:101]
	v_mfma_f32_16x16x32_bf16 v[86:89], v[222:225], v[206:209], v[86:89]
	v_mfma_f32_16x16x32_bf16 v[86:89], v[226:229], v[210:213], v[86:89]
	v_mfma_f32_16x16x32_bf16 v[82:85], v[230:233], v[206:209], v[82:85]
	v_mfma_f32_16x16x32_bf16 v[82:85], v[234:237], v[210:213], v[82:85]
	v_mfma_f32_16x16x32_bf16 v[70:73], v[222:225], v[214:217], v[70:73]
	v_mfma_f32_16x16x32_bf16 v[70:73], v[226:229], v[218:221], v[70:73]
	v_mfma_f32_16x16x32_bf16 v[66:69], v[230:233], v[214:217], v[66:69]
	s_barrier
	v_mfma_f32_16x16x32_bf16 v[66:69], v[234:237], v[218:221], v[66:69]
	s_setprio 0
	s_mov_b32 m0, s93
	s_mov_b64 s[100:101], s[60:61]
	ds_read_b128 v[190:193], v169 offset:16384
	ds_read_b128 v[194:197], v169 offset:17408
	ds_read_b128 v[198:201], v169 offset:18432
	ds_read_b128 v[202:205], v169 offset:19456
	ds_read_b128 v[206:209], v169 offset:20480
	ds_read_b128 v[210:213], v169 offset:21504
	ds_read_b128 v[214:217], v169 offset:22528
	ds_read_b128 v[218:221], v169 offset:23552
	global_load_lds_dwordx4 v136, s[60:61]
	s_mov_b64 s[100:101], s[60:61]
	s_mov_b32 m0, s98
	s_nop 0
	global_load_lds_dwordx4 v132, s[60:61]
	s_waitcnt vmcnt(8)
	s_barrier
	s_waitcnt lgkmcnt(0)
	s_setprio 1
	s_waitcnt lgkmcnt(0)
	v_mfma_f32_16x16x32_bf16 v[62:65], v[142:145], v[190:193], v[62:65]
	v_mfma_f32_16x16x32_bf16 v[62:65], v[162:165], v[194:197], v[62:65]
	v_mfma_f32_16x16x32_bf16 v[58:61], v[182:185], v[190:193], v[58:61]
	v_mfma_f32_16x16x32_bf16 v[58:61], v[186:189], v[194:197], v[58:61]
	v_mfma_f32_16x16x32_bf16 v[46:49], v[142:145], v[198:201], v[46:49]
	v_mfma_f32_16x16x32_bf16 v[46:49], v[162:165], v[202:205], v[46:49]
	v_mfma_f32_16x16x32_bf16 v[42:45], v[182:185], v[198:201], v[42:45]
	v_mfma_f32_16x16x32_bf16 v[42:45], v[186:189], v[202:205], v[42:45]
	v_mfma_f32_16x16x32_bf16 v[30:33], v[142:145], v[206:209], v[30:33]
	v_mfma_f32_16x16x32_bf16 v[30:33], v[162:165], v[210:213], v[30:33]
	v_mfma_f32_16x16x32_bf16 v[26:29], v[182:185], v[206:209], v[26:29]
	v_mfma_f32_16x16x32_bf16 v[26:29], v[186:189], v[210:213], v[26:29]
	v_mfma_f32_16x16x32_bf16 v[14:17], v[142:145], v[214:217], v[14:17]
	v_mfma_f32_16x16x32_bf16 v[14:17], v[162:165], v[218:221], v[14:17]
	v_mfma_f32_16x16x32_bf16 v[10:13], v[182:185], v[214:217], v[10:13]
	s_barrier
	v_mfma_f32_16x16x32_bf16 v[10:13], v[186:189], v[218:221], v[10:13]
	s_setprio 0
	s_add_u32 s24, s48, 0x40000
	s_addc_u32 s25, s49, 0
	s_add_i32 s51, s51, s86
	s_mov_b32 m0, s51
	s_nop 0
	global_load_lds_dwordx4 v134, s[24:25]
	s_add_i32 m0, s51, 0x2000
	s_nop 0
	global_load_lds_dwordx4 v130, s[24:25]
	s_waitcnt vmcnt(6)
	s_barrier
; #define PG8_STAGE(bufoff, gbase, voff) do { _Pragma("unroll") for (int _i = 0; _i < 2; ++_i) \
;         __builtin_amdgcn_global_load_lds((const unsigned*)((const char*)(gbase) + (voff)[_i]), (LAS unsigned*)(lds + (bufoff) + ldsw + _i * 8192), 16, 0, 0); } while (0)
; #define PG8_LDA(dst, b, h) do { _Pragma("unroll") for (int m = 0; m < 4; ++m) _Pragma("unroll") for (int k = 0; k < 2; ++k) dst[m][k] = *(const LAS bf16x8*)(lds + PG8_SA(b, h) + aoff + m * 2048 + k * 1024); } while (0)
; #define PG8_LDB(dst, b, h) do { _Pragma("unroll") for (int n = 0; n < 2; ++n) _Pragma("unroll") for (int k = 0; k < 2; ++k) dst[n][k] = *(const LAS bf16x8*)(lds + PG8_SB(b, h) + boff + n * 2048 + k * 1024); } while (0)
; #define PG8_MMA(ai, bj, At, Bt) do { __builtin_amdgcn_s_setprio(1); _Pragma("unroll") for (int m = 0; m < 4; ++m) _Pragma("unroll") for (int n = 0; n < 2; ++n) _Pragma("unroll") for (int k = 0; k < 2; ++k) \
;         acc[ai][bj][m][n] = __builtin_amdgcn_mfma_f32_16x16x32_bf16(Bt[n][k], At[m][k], acc[ai][bj][m][n], 0, 0, 0); __builtin_amdgcn_s_setprio(0); } while (0)
; #define PG8_WAIT_V(n) asm volatile("s_waitcnt vmcnt(" #n ")" ::: "memory")
; #define PG8_WAIT_L(n) asm volatile("s_waitcnt lgkmcnt(" #n ")" ::: "memory")
; #define PG8_BAR __builtin_amdgcn_s_barrier()
; #define PG8_SCHED __builtin_amdgcn_sched_barrier(0)
; template <class Epi, class Sched>
; __device__ __forceinline__ void gemm_phase(LAS unsigned char* lds, const Gemm g, const Sched& S, const Epi& E) {
;     ...
;             PG8_WAIT_V(6); PG8_BAR; PG8_MMA(1, 1, At, B1); PG8_BAR;
;             PG8_LDB(B0, 1, 0); PG8_SCHED; PG8_LDA(At, 1, 0); PG8_STAGE(PG8_SA(0, 1), a2 + hstep, voffA);
;             PG8_WAIT_L(8); PG8_BAR; PG8_WAIT_L(0); PG8_MMA(0, 0, At, B0); PG8_BAR; PG8_SCHED;
;             PG8_LDB(B1, 1, 1); PG8_STAGE(PG8_SB(1, 0), b3, voffB);
;             PG8_BAR; PG8_WAIT_L(0); PG8_MMA(0, 1, At, B1); PG8_BAR;
	s_setprio 1
	v_mfma_f32_16x16x32_bf16 v[54:57], v[222:225], v[190:193], v[54:57]
	ds_read_b128 v[142:145], v249 offset:32768
	ds_read_b128 v[162:165], v249 offset:33792
	v_mfma_f32_16x16x32_bf16 v[54:57], v[226:229], v[194:197], v[54:57]
	ds_read_b128 v[182:185], v249 offset:34816
	ds_read_b128 v[186:189], v249 offset:35840
	v_mfma_f32_16x16x32_bf16 v[50:53], v[230:233], v[190:193], v[50:53]
	ds_read_b128 v[190:193], v169 offset:32768
	v_mfma_f32_16x16x32_bf16 v[50:53], v[234:237], v[194:197], v[50:53]
	ds_read_b128 v[194:197], v169 offset:33792
	v_mfma_f32_16x16x32_bf16 v[38:41], v[222:225], v[198:201], v[38:41]
	v_mfma_f32_16x16x32_bf16 v[38:41], v[226:229], v[202:205], v[38:41]
	v_mfma_f32_16x16x32_bf16 v[34:37], v[230:233], v[198:201], v[34:37]
	ds_read_b128 v[198:201], v169 offset:34816
	v_mfma_f32_16x16x32_bf16 v[34:37], v[234:237], v[202:205], v[34:37]
	ds_read_b128 v[202:205], v169 offset:35840
	v_mfma_f32_16x16x32_bf16 v[22:25], v[222:225], v[206:209], v[22:25]
	v_mfma_f32_16x16x32_bf16 v[22:25], v[226:229], v[210:213], v[22:25]
	v_mfma_f32_16x16x32_bf16 v[18:21], v[230:233], v[206:209], v[18:21]
	ds_read_b128 v[206:209], v169 offset:36864
	v_mfma_f32_16x16x32_bf16 v[18:21], v[234:237], v[210:213], v[18:21]
	ds_read_b128 v[210:213], v169 offset:37888
	v_mfma_f32_16x16x32_bf16 v[6:9], v[222:225], v[214:217], v[6:9]
	v_mfma_f32_16x16x32_bf16 v[6:9], v[226:229], v[218:221], v[6:9]
	v_mfma_f32_16x16x32_bf16 v[2:5], v[230:233], v[214:217], v[2:5]
	s_barrier
	v_mfma_f32_16x16x32_bf16 v[2:5], v[234:237], v[218:221], v[2:5]
	s_setprio 0
	s_add_i32 s51, 0, 0x18000
	s_add_u32 s24, s60, 0x40000
	s_addc_u32 s25, s61, 0
	s_mov_b32 m0, s99
	ds_read_b128 v[214:217], v169 offset:38912
	ds_read_b128 v[218:221], v169 offset:39936
	global_load_lds_dwordx4 v136, s[24:25]
	s_mov_b32 m0, s94
	s_nop 0
	global_load_lds_dwordx4 v132, s[24:25]
	s_waitcnt lgkmcnt(8)
	s_barrier
	s_waitcnt lgkmcnt(0)
	s_setprio 1
	s_waitcnt lgkmcnt(0)
	v_mfma_f32_16x16x32_bf16 v[126:129], v[142:145], v[190:193], v[126:129]
	v_mfma_f32_16x16x32_bf16 v[126:129], v[162:165], v[194:197], v[126:129]
	v_mfma_f32_16x16x32_bf16 v[122:125], v[182:185], v[190:193], v[122:125]
	v_mfma_f32_16x16x32_bf16 v[122:125], v[186:189], v[194:197], v[122:125]
	v_mfma_f32_16x16x32_bf16 v[110:113], v[142:145], v[198:201], v[110:113]
	v_mfma_f32_16x16x32_bf16 v[110:113], v[162:165], v[202:205], v[110:113]
	v_mfma_f32_16x16x32_bf16 v[106:109], v[182:185], v[198:201], v[106:109]
	v_mfma_f32_16x16x32_bf16 v[106:109], v[186:189], v[202:205], v[106:109]
	v_mfma_f32_16x16x32_bf16 v[94:97], v[142:145], v[206:209], v[94:97]
	v_mfma_f32_16x16x32_bf16 v[94:97], v[162:165], v[210:213], v[94:97]
	v_mfma_f32_16x16x32_bf16 v[90:93], v[182:185], v[206:209], v[90:93]
	v_mfma_f32_16x16x32_bf16 v[90:93], v[186:189], v[210:213], v[90:93]
	v_mfma_f32_16x16x32_bf16 v[78:81], v[142:145], v[214:217], v[78:81]
	v_mfma_f32_16x16x32_bf16 v[78:81], v[162:165], v[218:221], v[78:81]
	v_mfma_f32_16x16x32_bf16 v[74:77], v[182:185], v[214:217], v[74:77]
	s_barrier
	v_mfma_f32_16x16x32_bf16 v[74:77], v[186:189], v[218:221], v[74:77]
	s_setprio 0
	s_add_i32 s60, 0, 0x1c000
	s_add_i32 s24, s51, s86
	s_add_i32 m0, s24, 0xffffff80
	ds_read_b128 v[222:225], v249 offset:49152
	ds_read_b128 v[226:229], v249 offset:50176
	ds_read_b128 v[230:233], v249 offset:51200
	ds_read_b128 v[234:237], v249 offset:52224
	global_load_lds_dwordx4 v134, s[48:49] offset:128
	s_add_i32 m0, s24, 0x1f80
	s_nop 0
	global_load_lds_dwordx4 v130, s[48:49] offset:128
	s_barrier
	s_waitcnt lgkmcnt(0)
	s_setprio 1
	s_waitcnt lgkmcnt(0)
	v_mfma_f32_16x16x32_bf16 v[118:121], v[222:225], v[190:193], v[118:121]
	v_mfma_f32_16x16x32_bf16 v[118:121], v[226:229], v[194:197], v[118:121]
	v_mfma_f32_16x16x32_bf16 v[114:117], v[230:233], v[190:193], v[114:117]
	v_mfma_f32_16x16x32_bf16 v[114:117], v[234:237], v[194:197], v[114:117]
	v_mfma_f32_16x16x32_bf16 v[102:105], v[222:225], v[198:201], v[102:105]
	v_mfma_f32_16x16x32_bf16 v[102:105], v[226:229], v[202:205], v[102:105]
	v_mfma_f32_16x16x32_bf16 v[98:101], v[230:233], v[198:201], v[98:101]
	v_mfma_f32_16x16x32_bf16 v[98:101], v[234:237], v[202:205], v[98:101]
	v_mfma_f32_16x16x32_bf16 v[86:89], v[222:225], v[206:209], v[86:89]
	v_mfma_f32_16x16x32_bf16 v[86:89], v[226:229], v[210:213], v[86:89]
	v_mfma_f32_16x16x32_bf16 v[82:85], v[230:233], v[206:209], v[82:85]
	v_mfma_f32_16x16x32_bf16 v[82:85], v[234:237], v[210:213], v[82:85]
	v_mfma_f32_16x16x32_bf16 v[70:73], v[222:225], v[214:217], v[70:73]
	v_mfma_f32_16x16x32_bf16 v[70:73], v[226:229], v[218:221], v[70:73]
	v_mfma_f32_16x16x32_bf16 v[66:69], v[230:233], v[214:217], v[66:69]
	s_barrier
; #define PG8_STAGE(bufoff, gbase, voff) do { _Pragma("unroll") for (int _i = 0; _i < 2; ++_i) \
;         __builtin_amdgcn_global_load_lds((const unsigned*)((const char*)(gbase) + (voff)[_i]), (LAS unsigned*)(lds + (bufoff) + ldsw + _i * 8192), 16, 0, 0); } while (0)
; #define PG8_LDA(dst, b, h) do { _Pragma("unroll") for (int m = 0; m < 4; ++m) _Pragma("unroll") for (int k = 0; k < 2; ++k) dst[m][k] = *(const LAS bf16x8*)(lds + PG8_SA(b, h) + aoff + m * 2048 + k * 1024); } while (0)
; #define PG8_MMA(ai, bj, At, Bt) do { __builtin_amdgcn_s_setprio(1); _Pragma("unroll") for (int m = 0; m < 4; ++m) _Pragma("unroll") for (int n = 0; n < 2; ++n) _Pragma("unroll") for (int k = 0; k < 2; ++k) \
;         acc[ai][bj][m][n] = __builtin_amdgcn_mfma_f32_16x16x32_bf16(Bt[n][k], At[m][k], acc[ai][bj][m][n], 0, 0, 0); __builtin_amdgcn_s_setprio(0); } while (0)
; #define PG8_WAIT_V(n) asm volatile("s_waitcnt vmcnt(" #n ")" ::: "memory")
; #define PG8_WAIT_L(n) asm volatile("s_waitcnt lgkmcnt(" #n ")" ::: "memory")
; #define PG8_BAR __builtin_amdgcn_s_barrier()
; #define PG8_SCHED __builtin_amdgcn_sched_barrier(0)
; template <class Epi, class Sched>
; __device__ __forceinline__ void gemm_phase(LAS unsigned char* lds, const Gemm g, const Sched& S, const Epi& E) {
;     ...
;             PG8_BAR; PG8_WAIT_L(0); PG8_MMA(0, 1, At, B1); PG8_BAR;
;             PG8_LDA(At, 1, 1); PG8_STAGE(PG8_SA(1, 0), a3, voffA);
;             PG8_BAR; PG8_WAIT_L(0); PG8_MMA(1, 0, At, B0); PG8_BAR; PG8_SCHED;
;             PG8_STAGE(PG8_SB(1, 1), b3 + hstep, voffB);
;             PG8_WAIT_V(6); PG8_BAR; PG8_MMA(1, 1, At, B1); PG8_BAR;
;         }
	v_mfma_f32_16x16x32_bf16 v[66:69], v[234:237], v[218:221], v[66:69]
	s_setprio 0
	s_add_i32 m0, s95, 0xffffff80
	ds_read_b128 v[190:193], v169 offset:49152
	ds_read_b128 v[194:197], v169 offset:50176
	ds_read_b128 v[198:201], v169 offset:51200
	ds_read_b128 v[202:205], v169 offset:52224
	ds_read_b128 v[206:209], v169 offset:53248
	ds_read_b128 v[210:213], v169 offset:54272
	ds_read_b128 v[214:217], v169 offset:55296
	ds_read_b128 v[218:221], v169 offset:56320
	global_load_lds_dwordx4 v136, s[100:101] offset:128
	s_add_i32 m0, s96, 0xffffff80
	s_nop 0
	global_load_lds_dwordx4 v132, s[100:101] offset:128
	s_waitcnt vmcnt(8)
	s_barrier
	s_waitcnt lgkmcnt(0)
	s_setprio 1
	s_waitcnt lgkmcnt(0)
	v_mfma_f32_16x16x32_bf16 v[62:65], v[142:145], v[190:193], v[62:65]
	v_mfma_f32_16x16x32_bf16 v[62:65], v[162:165], v[194:197], v[62:65]
	v_mfma_f32_16x16x32_bf16 v[58:61], v[182:185], v[190:193], v[58:61]
	v_mfma_f32_16x16x32_bf16 v[58:61], v[186:189], v[194:197], v[58:61]
	v_mfma_f32_16x16x32_bf16 v[46:49], v[142:145], v[198:201], v[46:49]
	v_mfma_f32_16x16x32_bf16 v[46:49], v[162:165], v[202:205], v[46:49]
	v_mfma_f32_16x16x32_bf16 v[42:45], v[182:185], v[198:201], v[42:45]
	v_mfma_f32_16x16x32_bf16 v[42:45], v[186:189], v[202:205], v[42:45]
	v_mfma_f32_16x16x32_bf16 v[30:33], v[142:145], v[206:209], v[30:33]
	v_mfma_f32_16x16x32_bf16 v[30:33], v[162:165], v[210:213], v[30:33]
	v_mfma_f32_16x16x32_bf16 v[26:29], v[182:185], v[206:209], v[26:29]
	v_mfma_f32_16x16x32_bf16 v[26:29], v[186:189], v[210:213], v[26:29]
	v_mfma_f32_16x16x32_bf16 v[14:17], v[142:145], v[214:217], v[14:17]
	v_mfma_f32_16x16x32_bf16 v[14:17], v[162:165], v[218:221], v[14:17]
	v_mfma_f32_16x16x32_bf16 v[10:13], v[182:185], v[214:217], v[10:13]
	s_barrier
	v_mfma_f32_16x16x32_bf16 v[10:13], v[186:189], v[218:221], v[10:13]
	s_setprio 0
	s_add_u32 s24, s48, 0x40080
	s_addc_u32 s25, s49, 0
	s_add_i32 s48, s60, s86
	s_mov_b32 m0, s48
	s_nop 0
	global_load_lds_dwordx4 v134, s[24:25]
	s_add_i32 m0, s48, 0x2000
	s_nop 0
	global_load_lds_dwordx4 v130, s[24:25]
	s_waitcnt vmcnt(6)
	s_barrier
	s_setprio 1
	v_mfma_f32_16x16x32_bf16 v[54:57], v[222:225], v[190:193], v[54:57]
	ds_read_b128 v[142:145], v249
	ds_read_b128 v[162:165], v249 offset:1024
	v_mfma_f32_16x16x32_bf16 v[54:57], v[226:229], v[194:197], v[54:57]
	ds_read_b128 v[182:185], v249 offset:2048
	ds_read_b128 v[186:189], v249 offset:3072
	v_mfma_f32_16x16x32_bf16 v[50:53], v[230:233], v[190:193], v[50:53]
	ds_read_b128 v[190:193], v169
	v_mfma_f32_16x16x32_bf16 v[50:53], v[234:237], v[194:197], v[50:53]
	ds_read_b128 v[194:197], v169 offset:1024
	v_mfma_f32_16x16x32_bf16 v[38:41], v[222:225], v[198:201], v[38:41]
	v_mfma_f32_16x16x32_bf16 v[38:41], v[226:229], v[202:205], v[38:41]
	v_mfma_f32_16x16x32_bf16 v[34:37], v[230:233], v[198:201], v[34:37]
	ds_read_b128 v[198:201], v169 offset:2048
	v_mfma_f32_16x16x32_bf16 v[34:37], v[234:237], v[202:205], v[34:37]
	ds_read_b128 v[202:205], v169 offset:3072
	v_mfma_f32_16x16x32_bf16 v[22:25], v[222:225], v[206:209], v[22:25]
	v_mfma_f32_16x16x32_bf16 v[22:25], v[226:229], v[210:213], v[22:25]
	v_mfma_f32_16x16x32_bf16 v[18:21], v[230:233], v[206:209], v[18:21]
	ds_read_b128 v[206:209], v169 offset:4096
	v_mfma_f32_16x16x32_bf16 v[18:21], v[234:237], v[210:213], v[18:21]
	ds_read_b128 v[210:213], v169 offset:5120
	v_mfma_f32_16x16x32_bf16 v[6:9], v[222:225], v[214:217], v[6:9]
	v_mfma_f32_16x16x32_bf16 v[6:9], v[226:229], v[218:221], v[6:9]
	v_mfma_f32_16x16x32_bf16 v[2:5], v[230:233], v[214:217], v[2:5]
	s_barrier
	v_mfma_f32_16x16x32_bf16 v[2:5], v[234:237], v[218:221], v[2:5]
	s_setprio 0
	s_add_i32 s50, s50, 2
	s_add_u32 vcc_lo, vcc_lo, 0x100
	s_addc_u32 s35, s35, 0
	s_add_u32 s38, s38, 0x100
	s_addc_u32 s39, s39, 0
	s_cmp_gt_u32 s50, 13
	s_cbranch_scc0 .LBB0_165
	s_waitcnt lgkmcnt(0)
	s_and_b64 vcc, exec, s[40:41]
	s_cbranch_vccz .LBB0_168
	s_barrier

; #define PG8_STAGE(bufoff, gbase, voff) do { _Pragma("unroll") for (int _i = 0; _i < 2; ++_i) \
;         __builtin_amdgcn_global_load_lds((const unsigned*)((const char*)(gbase) + (voff)[_i]), (LAS unsigned*)(lds + (bufoff) + ldsw + _i * 8192), 16, 0, 0); } while (0)
; #define PG8_LDA(dst, b, h) do { _Pragma("unroll") for (int m = 0; m < 4; ++m) _Pragma("unroll") for (int k = 0; k < 2; ++k) dst[m][k] = *(const LAS bf16x8*)(lds + PG8_SA(b, h) + aoff + m * 2048 + k * 1024); } while (0)
; #define PG8_LDB(dst, b, h) do { _Pragma("unroll") for (int n = 0; n < 2; ++n) _Pragma("unroll") for (int k = 0; k < 2; ++k) dst[n][k] = *(const LAS bf16x8*)(lds + PG8_SB(b, h) + boff + n * 2048 + k * 1024); } while (0)
; #define PG8_MMA(ai, bj, At, Bt) do { __builtin_amdgcn_s_setprio(1); _Pragma("unroll") for (int m = 0; m < 4; ++m) _Pragma("unroll") for (int n = 0; n < 2; ++n) _Pragma("unroll") for (int k = 0; k < 2; ++k) \
;         acc[ai][bj][m][n] = __builtin_amdgcn_mfma_f32_16x16x32_bf16(Bt[n][k], At[m][k], acc[ai][bj][m][n], 0, 0, 0); __builtin_amdgcn_s_setprio(0); } while (0)
; #define PG8_WAIT_V(n) asm volatile("s_waitcnt vmcnt(" #n ")" ::: "memory")
; #define PG8_WAIT_L(n) asm volatile("s_waitcnt lgkmcnt(" #n ")" ::: "memory")
; #define PG8_BAR __builtin_amdgcn_s_barrier()
; template <class Epi, class Sched>
; __device__ __forceinline__ void gemm_phase(LAS unsigned char* lds, const Gemm g, const Sched& S, const Epi& E) {
;     ...
;             const bool last = (t == nt - 2);
;             const char* a1 = cA + (size_t)(t + 1) * kstep;
;             const char* a2 = last ? nA : cA + (size_t)(t + 2) * kstep; const char* b2 = last ? nB : cB + (size_t)(t + 2) * kstep;
;             const char* a3 = a2 + kstep; const char* b3 = b2 + kstep;
;             PG8_LDB(B0, 0, 0); PG8_SCHED; PG8_LDA(At, 0, 0); PG8_STAGE(PG8_SA(1, 1), a1 + hstep, voffA);
;             PG8_WAIT_L(8); PG8_BAR; PG8_WAIT_L(0); PG8_MMA(0, 0, At, B0); PG8_BAR; PG8_SCHED;
;             PG8_LDB(B1, 0, 1); PG8_STAGE(PG8_SB(0, 0), b2, voffB);
;             PG8_BAR; PG8_WAIT_L(0); PG8_MMA(0, 1, At, B1); PG8_BAR;
;             PG8_LDA(At, 0, 1); PG8_STAGE(PG8_SA(0, 0), a2, voffA);
;             PG8_BAR; PG8_WAIT_L(0); PG8_MMA(1, 0, At, B0); PG8_BAR; PG8_SCHED;
;             PG8_STAGE(PG8_SB(0, 1), b2 + hstep, voffB);
;             PG8_WAIT_V(6); PG8_BAR; PG8_MMA(1, 1, At, B1); PG8_BAR;
.LBB0_416:
	s_add_u32 s24, s0, 0xfffc0080
	s_addc_u32 s25, s1, -1
	s_add_i32 s39, 0, 0x10000
	s_cmp_eq_u32 s38, 12
	s_cselect_b32 vcc_hi, s77, s25
	s_cselect_b32 vcc_lo, s76, s24
	s_cselect_b32 s37, s47, s50
	s_cselect_b32 s36, s61, s35
	s_add_i32 m0, s93, 0xc000
	ds_read_b128 v[218:221], v162 offset:6144
	ds_read_b128 v[222:225], v162 offset:7168
	global_load_lds_dwordx4 v140, s[0:1]
	s_add_i32 m0, s93, 0xe000
	s_nop 0
	global_load_lds_dwordx4 v138, s[0:1]
	s_waitcnt lgkmcnt(8)
	s_barrier
	s_waitcnt lgkmcnt(0)
	s_setprio 1
	s_waitcnt lgkmcnt(0)
	v_mfma_f32_16x16x32_bf16 v[126:129], v[164:167], v[194:197], v[126:129]
	v_mfma_f32_16x16x32_bf16 v[126:129], v[182:185], v[198:201], v[126:129]
	v_mfma_f32_16x16x32_bf16 v[122:125], v[186:189], v[194:197], v[122:125]
	v_mfma_f32_16x16x32_bf16 v[122:125], v[190:193], v[198:201], v[122:125]
	v_mfma_f32_16x16x32_bf16 v[118:121], v[164:167], v[202:205], v[118:121]
	v_mfma_f32_16x16x32_bf16 v[118:121], v[182:185], v[206:209], v[118:121]
	v_mfma_f32_16x16x32_bf16 v[110:113], v[186:189], v[202:205], v[110:113]
	v_mfma_f32_16x16x32_bf16 v[110:113], v[190:193], v[206:209], v[110:113]
	v_mfma_f32_16x16x32_bf16 v[102:105], v[164:167], v[210:213], v[102:105]
	v_mfma_f32_16x16x32_bf16 v[102:105], v[182:185], v[214:217], v[102:105]
	v_mfma_f32_16x16x32_bf16 v[94:97], v[186:189], v[210:213], v[94:97]
	v_mfma_f32_16x16x32_bf16 v[94:97], v[190:193], v[214:217], v[94:97]
	v_mfma_f32_16x16x32_bf16 v[86:89], v[164:167], v[218:221], v[86:89]
	v_mfma_f32_16x16x32_bf16 v[86:89], v[182:185], v[222:225], v[86:89]
	v_mfma_f32_16x16x32_bf16 v[78:81], v[186:189], v[218:221], v[78:81]
	s_barrier
	v_mfma_f32_16x16x32_bf16 v[78:81], v[190:193], v[222:225], v[78:81]
	s_setprio 0
	s_add_i32 s51, 0, 0x14000
	s_add_i32 s24, s39, s86
	ds_read_b128 v[226:229], v249 offset:16384
	ds_read_b128 v[230:233], v249 offset:17408
	ds_read_b128 v[234:237], v249 offset:18432
	ds_read_b128 v[238:241], v249 offset:19456
	s_mov_b32 m0, s24
	global_load_lds_dwordx4 v134, s[36:37]
	s_add_i32 m0, s24, 0x2000
	s_nop 0
	global_load_lds_dwordx4 v130, s[36:37]
	s_barrier
	s_waitcnt lgkmcnt(0)
	s_setprio 1
	s_waitcnt lgkmcnt(0)
	v_mfma_f32_16x16x32_bf16 v[114:117], v[226:229], v[194:197], v[114:117]
	v_mfma_f32_16x16x32_bf16 v[114:117], v[230:233], v[198:201], v[114:117]
	v_mfma_f32_16x16x32_bf16 v[106:109], v[234:237], v[194:197], v[106:109]
	v_mfma_f32_16x16x32_bf16 v[106:109], v[238:241], v[198:201], v[106:109]
	v_mfma_f32_16x16x32_bf16 v[98:101], v[226:229], v[202:205], v[98:101]
	v_mfma_f32_16x16x32_bf16 v[98:101], v[230:233], v[206:209], v[98:101]
	v_mfma_f32_16x16x32_bf16 v[90:93], v[234:237], v[202:205], v[90:93]
	v_mfma_f32_16x16x32_bf16 v[90:93], v[238:241], v[206:209], v[90:93]
	v_mfma_f32_16x16x32_bf16 v[82:85], v[226:229], v[210:213], v[82:85]
	v_mfma_f32_16x16x32_bf16 v[82:85], v[230:233], v[214:217], v[82:85]
	v_mfma_f32_16x16x32_bf16 v[74:77], v[234:237], v[210:213], v[74:77]
	v_mfma_f32_16x16x32_bf16 v[74:77], v[238:241], v[214:217], v[74:77]
	v_mfma_f32_16x16x32_bf16 v[70:73], v[226:229], v[218:221], v[70:73]
	v_mfma_f32_16x16x32_bf16 v[70:73], v[230:233], v[222:225], v[70:73]
	v_mfma_f32_16x16x32_bf16 v[66:69], v[234:237], v[218:221], v[66:69]
	s_barrier
	v_mfma_f32_16x16x32_bf16 v[66:69], v[238:241], v[222:225], v[66:69]
	s_setprio 0
	s_mov_b32 m0, s93
	ds_read_b128 v[194:197], v162 offset:16384
	ds_read_b128 v[198:201], v162 offset:17408
	ds_read_b128 v[202:205], v162 offset:18432
	ds_read_b128 v[206:209], v162 offset:19456
	ds_read_b128 v[210:213], v162 offset:20480
	ds_read_b128 v[214:217], v162 offset:21504
	ds_read_b128 v[218:221], v162 offset:22528
	ds_read_b128 v[222:225], v162 offset:23552
	global_load_lds_dwordx4 v136, vcc
	s_mov_b32 m0, s94
	s_nop 0
	global_load_lds_dwordx4 v132, vcc
	s_waitcnt vmcnt(8)
	s_barrier
	s_waitcnt lgkmcnt(0)
	s_setprio 1
	s_waitcnt lgkmcnt(0)
	v_mfma_f32_16x16x32_bf16 v[62:65], v[164:167], v[194:197], v[62:65]
	v_mfma_f32_16x16x32_bf16 v[62:65], v[182:185], v[198:201], v[62:65]
	v_mfma_f32_16x16x32_bf16 v[58:61], v[186:189], v[194:197], v[58:61]
	v_mfma_f32_16x16x32_bf16 v[58:61], v[190:193], v[198:201], v[58:61]
	v_mfma_f32_16x16x32_bf16 v[54:57], v[164:167], v[202:205], v[54:57]
	v_mfma_f32_16x16x32_bf16 v[54:57], v[182:185], v[206:209], v[54:57]
	v_mfma_f32_16x16x32_bf16 v[46:49], v[186:189], v[202:205], v[46:49]
	v_mfma_f32_16x16x32_bf16 v[46:49], v[190:193], v[206:209], v[46:49]
	v_mfma_f32_16x16x32_bf16 v[38:41], v[164:167], v[210:213], v[38:41]
	v_mfma_f32_16x16x32_bf16 v[38:41], v[182:185], v[214:217], v[38:41]
	v_mfma_f32_16x16x32_bf16 v[30:33], v[186:189], v[210:213], v[30:33]
	v_mfma_f32_16x16x32_bf16 v[30:33], v[190:193], v[214:217], v[30:33]
	v_mfma_f32_16x16x32_bf16 v[22:25], v[164:167], v[218:221], v[22:25]
	v_mfma_f32_16x16x32_bf16 v[22:25], v[182:185], v[222:225], v[22:25]
	v_mfma_f32_16x16x32_bf16 v[14:17], v[186:189], v[218:221], v[14:17]
	s_barrier
	v_mfma_f32_16x16x32_bf16 v[14:17], v[190:193], v[222:225], v[14:17]
	s_setprio 0
	s_add_u32 s24, s36, 0x40000
	s_addc_u32 s25, s37, 0
	s_add_i32 s39, s51, s86
	s_mov_b32 m0, s39
	s_nop 0
	global_load_lds_dwordx4 v134, s[24:25]
	s_add_i32 m0, s39, 0x2000
	s_nop 0
	global_load_lds_dwordx4 v130, s[24:25]
	s_waitcnt vmcnt(6)
	s_barrier
; #define PG8_STAGE(bufoff, gbase, voff) do { _Pragma("unroll") for (int _i = 0; _i < 2; ++_i) \
;         __builtin_amdgcn_global_load_lds((const unsigned*)((const char*)(gbase) + (voff)[_i]), (LAS unsigned*)(lds + (bufoff) + ldsw + _i * 8192), 16, 0, 0); } while (0)
; #define PG8_LDA(dst, b, h) do { _Pragma("unroll") for (int m = 0; m < 4; ++m) _Pragma("unroll") for (int k = 0; k < 2; ++k) dst[m][k] = *(const LAS bf16x8*)(lds + PG8_SA(b, h) + aoff + m * 2048 + k * 1024); } while (0)
; #define PG8_LDB(dst, b, h) do { _Pragma("unroll") for (int n = 0; n < 2; ++n) _Pragma("unroll") for (int k = 0; k < 2; ++k) dst[n][k] = *(const LAS bf16x8*)(lds + PG8_SB(b, h) + boff + n * 2048 + k * 1024); } while (0)
; #define PG8_MMA(ai, bj, At, Bt) do { __builtin_amdgcn_s_setprio(1); _Pragma("unroll") for (int m = 0; m < 4; ++m) _Pragma("unroll") for (int n = 0; n < 2; ++n) _Pragma("unroll") for (int k = 0; k < 2; ++k) \
;         acc[ai][bj][m][n] = __builtin_amdgcn_mfma_f32_16x16x32_bf16(Bt[n][k], At[m][k], acc[ai][bj][m][n], 0, 0, 0); __builtin_amdgcn_s_setprio(0); } while (0)
; #define PG8_WAIT_V(n) asm volatile("s_waitcnt vmcnt(" #n ")" ::: "memory")
; #define PG8_WAIT_L(n) asm volatile("s_waitcnt lgkmcnt(" #n ")" ::: "memory")
; #define PG8_BAR __builtin_amdgcn_s_barrier()
; #define PG8_SCHED __builtin_amdgcn_sched_barrier(0)
; template <class Epi, class Sched>
; __device__ __forceinline__ void gemm_phase(LAS unsigned char* lds, const Gemm g, const Sched& S, const Epi& E) {
;     ...
;             PG8_WAIT_V(6); PG8_BAR; PG8_MMA(1, 1, At, B1); PG8_BAR;
;             PG8_LDB(B0, 1, 0); PG8_SCHED; PG8_LDA(At, 1, 0); PG8_STAGE(PG8_SA(0, 1), a2 + hstep, voffA);
;             PG8_WAIT_L(8); PG8_BAR; PG8_WAIT_L(0); PG8_MMA(0, 0, At, B0); PG8_BAR; PG8_SCHED;
;             PG8_LDB(B1, 1, 1); PG8_STAGE(PG8_SB(1, 0), b3, voffB);
;             PG8_BAR; PG8_WAIT_L(0); PG8_MMA(0, 1, At, B1); PG8_BAR;
;             PG8_LDA(At, 1, 1); PG8_STAGE(PG8_SA(1, 0), a3, voffA);
	s_setprio 1
	v_mfma_f32_16x16x32_bf16 v[50:53], v[226:229], v[194:197], v[50:53]
	ds_read_b128 v[164:167], v249 offset:32768
	ds_read_b128 v[182:185], v249 offset:33792
	v_mfma_f32_16x16x32_bf16 v[50:53], v[230:233], v[198:201], v[50:53]
	ds_read_b128 v[186:189], v249 offset:34816
	ds_read_b128 v[190:193], v249 offset:35840
	v_mfma_f32_16x16x32_bf16 v[42:45], v[234:237], v[194:197], v[42:45]
	ds_read_b128 v[194:197], v162 offset:32768
	v_mfma_f32_16x16x32_bf16 v[42:45], v[238:241], v[198:201], v[42:45]
	ds_read_b128 v[198:201], v162 offset:33792
	v_mfma_f32_16x16x32_bf16 v[34:37], v[226:229], v[202:205], v[34:37]
	v_mfma_f32_16x16x32_bf16 v[34:37], v[230:233], v[206:209], v[34:37]
	v_mfma_f32_16x16x32_bf16 v[26:29], v[234:237], v[202:205], v[26:29]
	ds_read_b128 v[202:205], v162 offset:34816
	v_mfma_f32_16x16x32_bf16 v[26:29], v[238:241], v[206:209], v[26:29]
	ds_read_b128 v[206:209], v162 offset:35840
	v_mfma_f32_16x16x32_bf16 v[18:21], v[226:229], v[210:213], v[18:21]
	v_mfma_f32_16x16x32_bf16 v[18:21], v[230:233], v[214:217], v[18:21]
	v_mfma_f32_16x16x32_bf16 v[10:13], v[234:237], v[210:213], v[10:13]
	ds_read_b128 v[210:213], v162 offset:36864
	v_mfma_f32_16x16x32_bf16 v[10:13], v[238:241], v[214:217], v[10:13]
	ds_read_b128 v[214:217], v162 offset:37888
	v_mfma_f32_16x16x32_bf16 v[6:9], v[226:229], v[218:221], v[6:9]
	v_mfma_f32_16x16x32_bf16 v[6:9], v[230:233], v[222:225], v[6:9]
	v_mfma_f32_16x16x32_bf16 v[2:5], v[234:237], v[218:221], v[2:5]
	s_barrier
	v_mfma_f32_16x16x32_bf16 v[2:5], v[238:241], v[222:225], v[2:5]
	s_setprio 0
	s_add_i32 s39, 0, 0x18000
	s_add_u32 s24, vcc_lo, 0x40000
	s_addc_u32 s25, vcc_hi, 0
	s_mov_b32 m0, s95
	ds_read_b128 v[218:221], v162 offset:38912
	ds_read_b128 v[222:225], v162 offset:39936
	global_load_lds_dwordx4 v136, s[24:25]
	s_mov_b32 m0, s96
	s_nop 0
	global_load_lds_dwordx4 v132, s[24:25]
	s_waitcnt lgkmcnt(8)
	s_barrier
	s_waitcnt lgkmcnt(0)
	s_setprio 1
	s_waitcnt lgkmcnt(0)
	v_mfma_f32_16x16x32_bf16 v[126:129], v[164:167], v[194:197], v[126:129]
	v_mfma_f32_16x16x32_bf16 v[126:129], v[182:185], v[198:201], v[126:129]
	v_mfma_f32_16x16x32_bf16 v[122:125], v[186:189], v[194:197], v[122:125]
	v_mfma_f32_16x16x32_bf16 v[122:125], v[190:193], v[198:201], v[122:125]
	v_mfma_f32_16x16x32_bf16 v[118:121], v[164:167], v[202:205], v[118:121]
	v_mfma_f32_16x16x32_bf16 v[118:121], v[182:185], v[206:209], v[118:121]
	v_mfma_f32_16x16x32_bf16 v[110:113], v[186:189], v[202:205], v[110:113]
	v_mfma_f32_16x16x32_bf16 v[110:113], v[190:193], v[206:209], v[110:113]
	v_mfma_f32_16x16x32_bf16 v[102:105], v[164:167], v[210:213], v[102:105]
	v_mfma_f32_16x16x32_bf16 v[102:105], v[182:185], v[214:217], v[102:105]
	v_mfma_f32_16x16x32_bf16 v[94:97], v[186:189], v[210:213], v[94:97]
	v_mfma_f32_16x16x32_bf16 v[94:97], v[190:193], v[214:217], v[94:97]
	v_mfma_f32_16x16x32_bf16 v[86:89], v[164:167], v[218:221], v[86:89]
	v_mfma_f32_16x16x32_bf16 v[86:89], v[182:185], v[222:225], v[86:89]
	v_mfma_f32_16x16x32_bf16 v[78:81], v[186:189], v[218:221], v[78:81]
	s_barrier
	v_mfma_f32_16x16x32_bf16 v[78:81], v[190:193], v[222:225], v[78:81]
	s_setprio 0
	s_add_i32 s51, 0, 0x1c000
	s_add_i32 s24, s39, s86
	s_add_i32 m0, s24, 0xffffff80
	ds_read_b128 v[226:229], v249 offset:49152
	ds_read_b128 v[230:233], v249 offset:50176
	ds_read_b128 v[234:237], v249 offset:51200
	ds_read_b128 v[238:241], v249 offset:52224
	global_load_lds_dwordx4 v134, s[36:37] offset:128
	s_add_i32 m0, s24, 0x1f80
	s_nop 0
	global_load_lds_dwordx4 v130, s[36:37] offset:128
	s_barrier
	s_waitcnt lgkmcnt(0)
	s_setprio 1
	s_waitcnt lgkmcnt(0)
	v_mfma_f32_16x16x32_bf16 v[114:117], v[226:229], v[194:197], v[114:117]
	v_mfma_f32_16x16x32_bf16 v[114:117], v[230:233], v[198:201], v[114:117]
	v_mfma_f32_16x16x32_bf16 v[106:109], v[234:237], v[194:197], v[106:109]
	v_mfma_f32_16x16x32_bf16 v[106:109], v[238:241], v[198:201], v[106:109]
	v_mfma_f32_16x16x32_bf16 v[98:101], v[226:229], v[202:205], v[98:101]
	v_mfma_f32_16x16x32_bf16 v[98:101], v[230:233], v[206:209], v[98:101]
	v_mfma_f32_16x16x32_bf16 v[90:93], v[234:237], v[202:205], v[90:93]
	v_mfma_f32_16x16x32_bf16 v[90:93], v[238:241], v[206:209], v[90:93]
	v_mfma_f32_16x16x32_bf16 v[82:85], v[226:229], v[210:213], v[82:85]
	v_mfma_f32_16x16x32_bf16 v[82:85], v[230:233], v[214:217], v[82:85]
	v_mfma_f32_16x16x32_bf16 v[74:77], v[234:237], v[210:213], v[74:77]
	v_mfma_f32_16x16x32_bf16 v[74:77], v[238:241], v[214:217], v[74:77]
	v_mfma_f32_16x16x32_bf16 v[70:73], v[226:229], v[218:221], v[70:73]
	v_mfma_f32_16x16x32_bf16 v[70:73], v[230:233], v[222:225], v[70:73]
	v_mfma_f32_16x16x32_bf16 v[66:69], v[234:237], v[218:221], v[66:69]
	s_barrier
; #define PG8_STAGE(bufoff, gbase, voff) do { _Pragma("unroll") for (int _i = 0; _i < 2; ++_i) \
;         __builtin_amdgcn_global_load_lds((const unsigned*)((const char*)(gbase) + (voff)[_i]), (LAS unsigned*)(lds + (bufoff) + ldsw + _i * 8192), 16, 0, 0); } while (0)
; #define PG8_LDA(dst, b, h) do { _Pragma("unroll") for (int m = 0; m < 4; ++m) _Pragma("unroll") for (int k = 0; k < 2; ++k) dst[m][k] = *(const LAS bf16x8*)(lds + PG8_SA(b, h) + aoff + m * 2048 + k * 1024); } while (0)
; #define PG8_MMA(ai, bj, At, Bt) do { __builtin_amdgcn_s_setprio(1); _Pragma("unroll") for (int m = 0; m < 4; ++m) _Pragma("unroll") for (int n = 0; n < 2; ++n) _Pragma("unroll") for (int k = 0; k < 2; ++k) \
;         acc[ai][bj][m][n] = __builtin_amdgcn_mfma_f32_16x16x32_bf16(Bt[n][k], At[m][k], acc[ai][bj][m][n], 0, 0, 0); __builtin_amdgcn_s_setprio(0); } while (0)
; #define PG8_WAIT_V(n) asm volatile("s_waitcnt vmcnt(" #n ")" ::: "memory")
; #define PG8_WAIT_L(n) asm volatile("s_waitcnt lgkmcnt(" #n ")" ::: "memory")
; #define PG8_BAR __builtin_amdgcn_s_barrier()
; #define PG8_SCHED __builtin_amdgcn_sched_barrier(0)
; template <class Epi, class Sched>
; __device__ __forceinline__ void gemm_phase(LAS unsigned char* lds, const Gemm g, const Sched& S, const Epi& E) {
;     ...
;             PG8_LDA(At, 1, 1); PG8_STAGE(PG8_SA(1, 0), a3, voffA);
;             PG8_BAR; PG8_WAIT_L(0); PG8_MMA(1, 0, At, B0); PG8_BAR; PG8_SCHED;
;             PG8_STAGE(PG8_SB(1, 1), b3 + hstep, voffB);
;             PG8_WAIT_V(6); PG8_BAR; PG8_MMA(1, 1, At, B1); PG8_BAR;
;         }
	v_mfma_f32_16x16x32_bf16 v[66:69], v[238:241], v[222:225], v[66:69]
	s_setprio 0
	s_add_i32 m0, s97, 0xffffff80
	ds_read_b128 v[194:197], v162 offset:49152
	ds_read_b128 v[198:201], v162 offset:50176
	ds_read_b128 v[202:205], v162 offset:51200
	ds_read_b128 v[206:209], v162 offset:52224
	ds_read_b128 v[210:213], v162 offset:53248
	ds_read_b128 v[214:217], v162 offset:54272
	ds_read_b128 v[218:221], v162 offset:55296
	ds_read_b128 v[222:225], v162 offset:56320
	global_load_lds_dwordx4 v136, vcc offset:128
	s_add_i32 m0, s98, 0xffffff80
	s_nop 0
	global_load_lds_dwordx4 v132, vcc offset:128
	s_waitcnt vmcnt(8)
	s_barrier
	s_waitcnt lgkmcnt(0)
	s_setprio 1
	s_waitcnt lgkmcnt(0)
	v_mfma_f32_16x16x32_bf16 v[62:65], v[164:167], v[194:197], v[62:65]
	v_mfma_f32_16x16x32_bf16 v[62:65], v[182:185], v[198:201], v[62:65]
	v_mfma_f32_16x16x32_bf16 v[58:61], v[186:189], v[194:197], v[58:61]
	v_mfma_f32_16x16x32_bf16 v[58:61], v[190:193], v[198:201], v[58:61]
	v_mfma_f32_16x16x32_bf16 v[54:57], v[164:167], v[202:205], v[54:57]
	v_mfma_f32_16x16x32_bf16 v[54:57], v[182:185], v[206:209], v[54:57]
	v_mfma_f32_16x16x32_bf16 v[46:49], v[186:189], v[202:205], v[46:49]
	v_mfma_f32_16x16x32_bf16 v[46:49], v[190:193], v[206:209], v[46:49]
	v_mfma_f32_16x16x32_bf16 v[38:41], v[164:167], v[210:213], v[38:41]
	v_mfma_f32_16x16x32_bf16 v[38:41], v[182:185], v[214:217], v[38:41]
	v_mfma_f32_16x16x32_bf16 v[30:33], v[186:189], v[210:213], v[30:33]
	v_mfma_f32_16x16x32_bf16 v[30:33], v[190:193], v[214:217], v[30:33]
	v_mfma_f32_16x16x32_bf16 v[22:25], v[164:167], v[218:221], v[22:25]
	v_mfma_f32_16x16x32_bf16 v[22:25], v[182:185], v[222:225], v[22:25]
	v_mfma_f32_16x16x32_bf16 v[14:17], v[186:189], v[218:221], v[14:17]
	s_barrier
	v_mfma_f32_16x16x32_bf16 v[14:17], v[190:193], v[222:225], v[14:17]
	s_setprio 0
	s_add_u32 s24, s36, 0x40080
	s_addc_u32 s25, s37, 0
	s_add_i32 s36, s51, s86
	s_mov_b32 m0, s36
	s_nop 0
	global_load_lds_dwordx4 v134, s[24:25]
	s_add_i32 m0, s36, 0x2000
	s_nop 0
	global_load_lds_dwordx4 v130, s[24:25]
	s_waitcnt vmcnt(6)
	s_barrier
	s_setprio 1
	v_mfma_f32_16x16x32_bf16 v[50:53], v[226:229], v[194:197], v[50:53]
	ds_read_b128 v[164:167], v249
	ds_read_b128 v[182:185], v249 offset:1024
	v_mfma_f32_16x16x32_bf16 v[50:53], v[230:233], v[198:201], v[50:53]
	ds_read_b128 v[186:189], v249 offset:2048
	ds_read_b128 v[190:193], v249 offset:3072
	v_mfma_f32_16x16x32_bf16 v[42:45], v[234:237], v[194:197], v[42:45]
	ds_read_b128 v[194:197], v162
	v_mfma_f32_16x16x32_bf16 v[42:45], v[238:241], v[198:201], v[42:45]
	ds_read_b128 v[198:201], v162 offset:1024
	v_mfma_f32_16x16x32_bf16 v[34:37], v[226:229], v[202:205], v[34:37]
	v_mfma_f32_16x16x32_bf16 v[34:37], v[230:233], v[206:209], v[34:37]
	v_mfma_f32_16x16x32_bf16 v[26:29], v[234:237], v[202:205], v[26:29]
	ds_read_b128 v[202:205], v162 offset:2048
	v_mfma_f32_16x16x32_bf16 v[26:29], v[238:241], v[206:209], v[26:29]
	ds_read_b128 v[206:209], v162 offset:3072
	v_mfma_f32_16x16x32_bf16 v[18:21], v[226:229], v[210:213], v[18:21]
	v_mfma_f32_16x16x32_bf16 v[18:21], v[230:233], v[214:217], v[18:21]
	v_mfma_f32_16x16x32_bf16 v[10:13], v[234:237], v[210:213], v[10:13]
	ds_read_b128 v[210:213], v162 offset:4096
	v_mfma_f32_16x16x32_bf16 v[10:13], v[238:241], v[214:217], v[10:13]
	ds_read_b128 v[214:217], v162 offset:5120
	v_mfma_f32_16x16x32_bf16 v[6:9], v[226:229], v[218:221], v[6:9]
	v_mfma_f32_16x16x32_bf16 v[6:9], v[230:233], v[222:225], v[6:9]
	v_mfma_f32_16x16x32_bf16 v[2:5], v[234:237], v[218:221], v[2:5]
	s_barrier
	v_mfma_f32_16x16x32_bf16 v[2:5], v[238:241], v[222:225], v[2:5]
	s_setprio 0
	s_add_i32 s38, s38, 2
	s_add_u32 s35, s35, 0x100
	s_addc_u32 s50, s50, 0
	s_add_u32 s0, s0, 0x100
	s_addc_u32 s1, s1, 0
	s_cmp_gt_u32 s38, 13
	s_cbranch_scc0 .LBB0_416
	s_waitcnt lgkmcnt(0)
	s_and_b64 vcc, exec, s[44:45]
	s_cbranch_vccz .LBB0_419
	s_barrier

; #define PG8_STAGE(bufoff, gbase, voff) do { _Pragma("unroll") for (int _i = 0; _i < 2; ++_i) \
;         __builtin_amdgcn_global_load_lds((const unsigned*)((const char*)(gbase) + (voff)[_i]), (LAS unsigned*)(lds + (bufoff) + ldsw + _i * 8192), 16, 0, 0); } while (0)
; #define PG8_LDA(dst, b, h) do { _Pragma("unroll") for (int m = 0; m < 4; ++m) _Pragma("unroll") for (int k = 0; k < 2; ++k) dst[m][k] = *(const LAS bf16x8*)(lds + PG8_SA(b, h) + aoff + m * 2048 + k * 1024); } while (0)
; #define PG8_LDB(dst, b, h) do { _Pragma("unroll") for (int n = 0; n < 2; ++n) _Pragma("unroll") for (int k = 0; k < 2; ++k) dst[n][k] = *(const LAS bf16x8*)(lds + PG8_SB(b, h) + boff + n * 2048 + k * 1024); } while (0)
; #define PG8_MMA(ai, bj, At, Bt) do { __builtin_amdgcn_s_setprio(1); _Pragma("unroll") for (int m = 0; m < 4; ++m) _Pragma("unroll") for (int n = 0; n < 2; ++n) _Pragma("unroll") for (int k = 0; k < 2; ++k) \
;         acc[ai][bj][m][n] = __builtin_amdgcn_mfma_f32_16x16x32_bf16(Bt[n][k], At[m][k], acc[ai][bj][m][n], 0, 0, 0); __builtin_amdgcn_s_setprio(0); } while (0)
; #define PG8_WAIT_V(n) asm volatile("s_waitcnt vmcnt(" #n ")" ::: "memory")
; #define PG8_WAIT_L(n) asm volatile("s_waitcnt lgkmcnt(" #n ")" ::: "memory")
; #define PG8_BAR __builtin_amdgcn_s_barrier()
; template <class Epi, class Sched>
; __device__ __forceinline__ void gemm_phase(LAS unsigned char* lds, const Gemm g, const Sched& S, const Epi& E) {
;     ...
;             const bool last = (t == nt - 2);
;             const char* a1 = cA + (size_t)(t + 1) * kstep;
;             const char* a2 = last ? nA : cA + (size_t)(t + 2) * kstep; const char* b2 = last ? nB : cB + (size_t)(t + 2) * kstep;
;             const char* a3 = a2 + kstep; const char* b3 = b2 + kstep;
;             PG8_LDB(B0, 0, 0); PG8_SCHED; PG8_LDA(At, 0, 0); PG8_STAGE(PG8_SA(1, 1), a1 + hstep, voffA);
;             PG8_WAIT_L(8); PG8_BAR; PG8_WAIT_L(0); PG8_MMA(0, 0, At, B0); PG8_BAR; PG8_SCHED;
;             PG8_LDB(B1, 0, 1); PG8_STAGE(PG8_SB(0, 0), b2, voffB);
;             PG8_BAR; PG8_WAIT_L(0); PG8_MMA(0, 1, At, B1); PG8_BAR;
;             PG8_LDA(At, 0, 1); PG8_STAGE(PG8_SA(0, 0), a2, voffA);
;             PG8_BAR; PG8_WAIT_L(0); PG8_MMA(1, 0, At, B0); PG8_BAR; PG8_SCHED;
;             PG8_STAGE(PG8_SB(0, 1), b2 + hstep, voffB);
;             PG8_WAIT_V(6); PG8_BAR; PG8_MMA(1, 1, At, B1); PG8_BAR;
.LBB0_557:
	s_add_u32 s24, s0, 0xfffc0080
	s_addc_u32 s25, s1, -1
	s_add_i32 s39, 0, 0x10000
	s_cmp_eq_u32 s38, 12
	s_cselect_b32 vcc_hi, s77, s25
	s_cselect_b32 vcc_lo, s76, s24
	s_cselect_b32 s49, s45, s50
	s_cselect_b32 s48, s47, s35
	s_add_i32 m0, s95, 0xc000
	ds_read_b128 v[218:221], v166 offset:6144
	ds_read_b128 v[222:225], v166 offset:7168
	global_load_lds_dwordx4 v140, s[0:1]
	s_add_i32 m0, s95, 0xe000
	s_nop 0
	global_load_lds_dwordx4 v138, s[0:1]
	s_waitcnt lgkmcnt(8)
	s_barrier
	s_waitcnt lgkmcnt(0)
	s_setprio 1
	s_waitcnt lgkmcnt(0)
	v_mfma_f32_16x16x32_bf16 v[126:129], v[142:145], v[194:197], v[126:129]
	v_mfma_f32_16x16x32_bf16 v[126:129], v[182:185], v[198:201], v[126:129]
	v_mfma_f32_16x16x32_bf16 v[122:125], v[186:189], v[194:197], v[122:125]
	v_mfma_f32_16x16x32_bf16 v[122:125], v[190:193], v[198:201], v[122:125]
	v_mfma_f32_16x16x32_bf16 v[110:113], v[142:145], v[202:205], v[110:113]
	v_mfma_f32_16x16x32_bf16 v[110:113], v[182:185], v[206:209], v[110:113]
	v_mfma_f32_16x16x32_bf16 v[106:109], v[186:189], v[202:205], v[106:109]
	v_mfma_f32_16x16x32_bf16 v[106:109], v[190:193], v[206:209], v[106:109]
	v_mfma_f32_16x16x32_bf16 v[94:97], v[142:145], v[210:213], v[94:97]
	v_mfma_f32_16x16x32_bf16 v[94:97], v[182:185], v[214:217], v[94:97]
	v_mfma_f32_16x16x32_bf16 v[90:93], v[186:189], v[210:213], v[90:93]
	v_mfma_f32_16x16x32_bf16 v[90:93], v[190:193], v[214:217], v[90:93]
	v_mfma_f32_16x16x32_bf16 v[78:81], v[142:145], v[218:221], v[78:81]
	v_mfma_f32_16x16x32_bf16 v[78:81], v[182:185], v[222:225], v[78:81]
	v_mfma_f32_16x16x32_bf16 v[74:77], v[186:189], v[218:221], v[74:77]
	s_barrier
	v_mfma_f32_16x16x32_bf16 v[74:77], v[190:193], v[222:225], v[74:77]
	s_setprio 0
	s_add_i32 s51, 0, 0x14000
	s_add_i32 s24, s39, s94
	ds_read_b128 v[226:229], v249 offset:16384
	ds_read_b128 v[230:233], v249 offset:17408
	ds_read_b128 v[234:237], v249 offset:18432
	ds_read_b128 v[238:241], v249 offset:19456
	s_mov_b32 m0, s24
	global_load_lds_dwordx4 v134, s[48:49]
	s_add_i32 m0, s24, 0x2000
	s_nop 0
	global_load_lds_dwordx4 v130, s[48:49]
	s_barrier
	s_waitcnt lgkmcnt(0)
	s_setprio 1
	s_waitcnt lgkmcnt(0)
	v_mfma_f32_16x16x32_bf16 v[118:121], v[226:229], v[194:197], v[118:121]
	v_mfma_f32_16x16x32_bf16 v[118:121], v[230:233], v[198:201], v[118:121]
	v_mfma_f32_16x16x32_bf16 v[114:117], v[234:237], v[194:197], v[114:117]
	v_mfma_f32_16x16x32_bf16 v[114:117], v[238:241], v[198:201], v[114:117]
	v_mfma_f32_16x16x32_bf16 v[102:105], v[226:229], v[202:205], v[102:105]
	v_mfma_f32_16x16x32_bf16 v[102:105], v[230:233], v[206:209], v[102:105]
	v_mfma_f32_16x16x32_bf16 v[98:101], v[234:237], v[202:205], v[98:101]
	v_mfma_f32_16x16x32_bf16 v[98:101], v[238:241], v[206:209], v[98:101]
	v_mfma_f32_16x16x32_bf16 v[86:89], v[226:229], v[210:213], v[86:89]
	v_mfma_f32_16x16x32_bf16 v[86:89], v[230:233], v[214:217], v[86:89]
	v_mfma_f32_16x16x32_bf16 v[82:85], v[234:237], v[210:213], v[82:85]
	v_mfma_f32_16x16x32_bf16 v[82:85], v[238:241], v[214:217], v[82:85]
	v_mfma_f32_16x16x32_bf16 v[70:73], v[226:229], v[218:221], v[70:73]
	v_mfma_f32_16x16x32_bf16 v[70:73], v[230:233], v[222:225], v[70:73]
	v_mfma_f32_16x16x32_bf16 v[66:69], v[234:237], v[218:221], v[66:69]
	s_barrier
	v_mfma_f32_16x16x32_bf16 v[66:69], v[238:241], v[222:225], v[66:69]
	s_setprio 0
	s_mov_b32 m0, s95
	ds_read_b128 v[194:197], v166 offset:16384
	ds_read_b128 v[198:201], v166 offset:17408
	ds_read_b128 v[202:205], v166 offset:18432
	ds_read_b128 v[206:209], v166 offset:19456
	ds_read_b128 v[210:213], v166 offset:20480
	ds_read_b128 v[214:217], v166 offset:21504
	ds_read_b128 v[218:221], v166 offset:22528
	ds_read_b128 v[222:225], v166 offset:23552
	global_load_lds_dwordx4 v136, vcc
	s_mov_b32 m0, s96
	s_nop 0
	global_load_lds_dwordx4 v132, vcc
	s_waitcnt vmcnt(8)
	s_barrier
	s_waitcnt lgkmcnt(0)
	s_setprio 1
	s_waitcnt lgkmcnt(0)
	v_mfma_f32_16x16x32_bf16 v[62:65], v[142:145], v[194:197], v[62:65]
	v_mfma_f32_16x16x32_bf16 v[62:65], v[182:185], v[198:201], v[62:65]
	v_mfma_f32_16x16x32_bf16 v[58:61], v[186:189], v[194:197], v[58:61]
	v_mfma_f32_16x16x32_bf16 v[58:61], v[190:193], v[198:201], v[58:61]
	v_mfma_f32_16x16x32_bf16 v[46:49], v[142:145], v[202:205], v[46:49]
	v_mfma_f32_16x16x32_bf16 v[46:49], v[182:185], v[206:209], v[46:49]
	v_mfma_f32_16x16x32_bf16 v[42:45], v[186:189], v[202:205], v[42:45]
	v_mfma_f32_16x16x32_bf16 v[42:45], v[190:193], v[206:209], v[42:45]
	v_mfma_f32_16x16x32_bf16 v[30:33], v[142:145], v[210:213], v[30:33]
	v_mfma_f32_16x16x32_bf16 v[30:33], v[182:185], v[214:217], v[30:33]
	v_mfma_f32_16x16x32_bf16 v[26:29], v[186:189], v[210:213], v[26:29]
	v_mfma_f32_16x16x32_bf16 v[26:29], v[190:193], v[214:217], v[26:29]
	v_mfma_f32_16x16x32_bf16 v[14:17], v[142:145], v[218:221], v[14:17]
	v_mfma_f32_16x16x32_bf16 v[14:17], v[182:185], v[222:225], v[14:17]
	v_mfma_f32_16x16x32_bf16 v[10:13], v[186:189], v[218:221], v[10:13]
	s_barrier
	v_mfma_f32_16x16x32_bf16 v[10:13], v[190:193], v[222:225], v[10:13]
	s_setprio 0
	s_add_u32 s24, s48, 0x40000
	s_addc_u32 s25, s49, 0
	s_add_i32 s39, s51, s94
	s_mov_b32 m0, s39
	s_nop 0
	global_load_lds_dwordx4 v134, s[24:25]
	s_add_i32 m0, s39, 0x2000
	s_nop 0
	global_load_lds_dwordx4 v130, s[24:25]
	s_waitcnt vmcnt(6)
	s_barrier
; #define PG8_STAGE(bufoff, gbase, voff) do { _Pragma("unroll") for (int _i = 0; _i < 2; ++_i) \
;         __builtin_amdgcn_global_load_lds((const unsigned*)((const char*)(gbase) + (voff)[_i]), (LAS unsigned*)(lds + (bufoff) + ldsw + _i * 8192), 16, 0, 0); } while (0)
; #define PG8_LDA(dst, b, h) do { _Pragma("unroll") for (int m = 0; m < 4; ++m) _Pragma("unroll") for (int k = 0; k < 2; ++k) dst[m][k] = *(const LAS bf16x8*)(lds + PG8_SA(b, h) + aoff + m * 2048 + k * 1024); } while (0)
; #define PG8_LDB(dst, b, h) do { _Pragma("unroll") for (int n = 0; n < 2; ++n) _Pragma("unroll") for (int k = 0; k < 2; ++k) dst[n][k] = *(const LAS bf16x8*)(lds + PG8_SB(b, h) + boff + n * 2048 + k * 1024); } while (0)
; #define PG8_MMA(ai, bj, At, Bt) do { __builtin_amdgcn_s_setprio(1); _Pragma("unroll") for (int m = 0; m < 4; ++m) _Pragma("unroll") for (int n = 0; n < 2; ++n) _Pragma("unroll") for (int k = 0; k < 2; ++k) \
;         acc[ai][bj][m][n] = __builtin_amdgcn_mfma_f32_16x16x32_bf16(Bt[n][k], At[m][k], acc[ai][bj][m][n], 0, 0, 0); __builtin_amdgcn_s_setprio(0); } while (0)
; #define PG8_WAIT_V(n) asm volatile("s_waitcnt vmcnt(" #n ")" ::: "memory")
; #define PG8_WAIT_L(n) asm volatile("s_waitcnt lgkmcnt(" #n ")" ::: "memory")
; #define PG8_BAR __builtin_amdgcn_s_barrier()
; #define PG8_SCHED __builtin_amdgcn_sched_barrier(0)
; template <class Epi, class Sched>
; __device__ __forceinline__ void gemm_phase(LAS unsigned char* lds, const Gemm g, const Sched& S, const Epi& E) {
;     ...
;             PG8_WAIT_V(6); PG8_BAR; PG8_MMA(1, 1, At, B1); PG8_BAR;
;             PG8_LDB(B0, 1, 0); PG8_SCHED; PG8_LDA(At, 1, 0); PG8_STAGE(PG8_SA(0, 1), a2 + hstep, voffA);
;             PG8_WAIT_L(8); PG8_BAR; PG8_WAIT_L(0); PG8_MMA(0, 0, At, B0); PG8_BAR; PG8_SCHED;
;             PG8_LDB(B1, 1, 1); PG8_STAGE(PG8_SB(1, 0), b3, voffB);
;             PG8_BAR; PG8_WAIT_L(0); PG8_MMA(0, 1, At, B1); PG8_BAR;
;             PG8_LDA(At, 1, 1); PG8_STAGE(PG8_SA(1, 0), a3, voffA);
	s_setprio 1
	v_mfma_f32_16x16x32_bf16 v[54:57], v[226:229], v[194:197], v[54:57]
	ds_read_b128 v[142:145], v249 offset:32768
	ds_read_b128 v[182:185], v249 offset:33792
	v_mfma_f32_16x16x32_bf16 v[54:57], v[230:233], v[198:201], v[54:57]
	ds_read_b128 v[186:189], v249 offset:34816
	ds_read_b128 v[190:193], v249 offset:35840
	v_mfma_f32_16x16x32_bf16 v[50:53], v[234:237], v[194:197], v[50:53]
	ds_read_b128 v[194:197], v166 offset:32768
	v_mfma_f32_16x16x32_bf16 v[50:53], v[238:241], v[198:201], v[50:53]
	ds_read_b128 v[198:201], v166 offset:33792
	v_mfma_f32_16x16x32_bf16 v[38:41], v[226:229], v[202:205], v[38:41]
	v_mfma_f32_16x16x32_bf16 v[38:41], v[230:233], v[206:209], v[38:41]
	v_mfma_f32_16x16x32_bf16 v[34:37], v[234:237], v[202:205], v[34:37]
	ds_read_b128 v[202:205], v166 offset:34816
	v_mfma_f32_16x16x32_bf16 v[34:37], v[238:241], v[206:209], v[34:37]
	ds_read_b128 v[206:209], v166 offset:35840
	v_mfma_f32_16x16x32_bf16 v[22:25], v[226:229], v[210:213], v[22:25]
	v_mfma_f32_16x16x32_bf16 v[22:25], v[230:233], v[214:217], v[22:25]
	v_mfma_f32_16x16x32_bf16 v[18:21], v[234:237], v[210:213], v[18:21]
	ds_read_b128 v[210:213], v166 offset:36864
	v_mfma_f32_16x16x32_bf16 v[18:21], v[238:241], v[214:217], v[18:21]
	ds_read_b128 v[214:217], v166 offset:37888
	v_mfma_f32_16x16x32_bf16 v[6:9], v[226:229], v[218:221], v[6:9]
	v_mfma_f32_16x16x32_bf16 v[6:9], v[230:233], v[222:225], v[6:9]
	v_mfma_f32_16x16x32_bf16 v[2:5], v[234:237], v[218:221], v[2:5]
	s_barrier
	v_mfma_f32_16x16x32_bf16 v[2:5], v[238:241], v[222:225], v[2:5]
	s_setprio 0
	s_add_i32 s39, 0, 0x18000
	s_add_u32 s24, vcc_lo, 0x40000
	s_addc_u32 s25, vcc_hi, 0
	s_mov_b32 m0, s97
	ds_read_b128 v[218:221], v166 offset:38912
	ds_read_b128 v[222:225], v166 offset:39936
	global_load_lds_dwordx4 v136, s[24:25]
	s_mov_b32 m0, s98
	s_nop 0
	global_load_lds_dwordx4 v132, s[24:25]
	s_waitcnt lgkmcnt(8)
	s_barrier
	s_waitcnt lgkmcnt(0)
	s_setprio 1
	s_waitcnt lgkmcnt(0)
	v_mfma_f32_16x16x32_bf16 v[126:129], v[142:145], v[194:197], v[126:129]
	v_mfma_f32_16x16x32_bf16 v[126:129], v[182:185], v[198:201], v[126:129]
	v_mfma_f32_16x16x32_bf16 v[122:125], v[186:189], v[194:197], v[122:125]
	v_mfma_f32_16x16x32_bf16 v[122:125], v[190:193], v[198:201], v[122:125]
	v_mfma_f32_16x16x32_bf16 v[110:113], v[142:145], v[202:205], v[110:113]
	v_mfma_f32_16x16x32_bf16 v[110:113], v[182:185], v[206:209], v[110:113]
	v_mfma_f32_16x16x32_bf16 v[106:109], v[186:189], v[202:205], v[106:109]
	v_mfma_f32_16x16x32_bf16 v[106:109], v[190:193], v[206:209], v[106:109]
	v_mfma_f32_16x16x32_bf16 v[94:97], v[142:145], v[210:213], v[94:97]
	v_mfma_f32_16x16x32_bf16 v[94:97], v[182:185], v[214:217], v[94:97]
	v_mfma_f32_16x16x32_bf16 v[90:93], v[186:189], v[210:213], v[90:93]
	v_mfma_f32_16x16x32_bf16 v[90:93], v[190:193], v[214:217], v[90:93]
	v_mfma_f32_16x16x32_bf16 v[78:81], v[142:145], v[218:221], v[78:81]
	v_mfma_f32_16x16x32_bf16 v[78:81], v[182:185], v[222:225], v[78:81]
	v_mfma_f32_16x16x32_bf16 v[74:77], v[186:189], v[218:221], v[74:77]
	s_barrier
	v_mfma_f32_16x16x32_bf16 v[74:77], v[190:193], v[222:225], v[74:77]
	s_setprio 0
	s_add_i32 s51, 0, 0x1c000
	s_add_i32 s24, s39, s94
	s_add_i32 m0, s24, 0xffffff80
	ds_read_b128 v[226:229], v249 offset:49152
	ds_read_b128 v[230:233], v249 offset:50176
	ds_read_b128 v[234:237], v249 offset:51200
	ds_read_b128 v[238:241], v249 offset:52224
	global_load_lds_dwordx4 v134, s[48:49] offset:128
	s_add_i32 m0, s24, 0x1f80
	s_nop 0
	global_load_lds_dwordx4 v130, s[48:49] offset:128
	s_barrier
	s_waitcnt lgkmcnt(0)
	s_setprio 1
	s_waitcnt lgkmcnt(0)
	v_mfma_f32_16x16x32_bf16 v[118:121], v[226:229], v[194:197], v[118:121]
	v_mfma_f32_16x16x32_bf16 v[118:121], v[230:233], v[198:201], v[118:121]
	v_mfma_f32_16x16x32_bf16 v[114:117], v[234:237], v[194:197], v[114:117]
	v_mfma_f32_16x16x32_bf16 v[114:117], v[238:241], v[198:201], v[114:117]
	v_mfma_f32_16x16x32_bf16 v[102:105], v[226:229], v[202:205], v[102:105]
	v_mfma_f32_16x16x32_bf16 v[102:105], v[230:233], v[206:209], v[102:105]
	v_mfma_f32_16x16x32_bf16 v[98:101], v[234:237], v[202:205], v[98:101]
	v_mfma_f32_16x16x32_bf16 v[98:101], v[238:241], v[206:209], v[98:101]
	v_mfma_f32_16x16x32_bf16 v[86:89], v[226:229], v[210:213], v[86:89]
	v_mfma_f32_16x16x32_bf16 v[86:89], v[230:233], v[214:217], v[86:89]
	v_mfma_f32_16x16x32_bf16 v[82:85], v[234:237], v[210:213], v[82:85]
	v_mfma_f32_16x16x32_bf16 v[82:85], v[238:241], v[214:217], v[82:85]
	v_mfma_f32_16x16x32_bf16 v[70:73], v[226:229], v[218:221], v[70:73]
	v_mfma_f32_16x16x32_bf16 v[70:73], v[230:233], v[222:225], v[70:73]
	v_mfma_f32_16x16x32_bf16 v[66:69], v[234:237], v[218:221], v[66:69]
	s_barrier
; #define PG8_STAGE(bufoff, gbase, voff) do { _Pragma("unroll") for (int _i = 0; _i < 2; ++_i) \
;         __builtin_amdgcn_global_load_lds((const unsigned*)((const char*)(gbase) + (voff)[_i]), (LAS unsigned*)(lds + (bufoff) + ldsw + _i * 8192), 16, 0, 0); } while (0)
; #define PG8_LDA(dst, b, h) do { _Pragma("unroll") for (int m = 0; m < 4; ++m) _Pragma("unroll") for (int k = 0; k < 2; ++k) dst[m][k] = *(const LAS bf16x8*)(lds + PG8_SA(b, h) + aoff + m * 2048 + k * 1024); } while (0)
; #define PG8_MMA(ai, bj, At, Bt) do { __builtin_amdgcn_s_setprio(1); _Pragma("unroll") for (int m = 0; m < 4; ++m) _Pragma("unroll") for (int n = 0; n < 2; ++n) _Pragma("unroll") for (int k = 0; k < 2; ++k) \
;         acc[ai][bj][m][n] = __builtin_amdgcn_mfma_f32_16x16x32_bf16(Bt[n][k], At[m][k], acc[ai][bj][m][n], 0, 0, 0); __builtin_amdgcn_s_setprio(0); } while (0)
; #define PG8_WAIT_V(n) asm volatile("s_waitcnt vmcnt(" #n ")" ::: "memory")
; #define PG8_WAIT_L(n) asm volatile("s_waitcnt lgkmcnt(" #n ")" ::: "memory")
; #define PG8_BAR __builtin_amdgcn_s_barrier()
; #define PG8_SCHED __builtin_amdgcn_sched_barrier(0)
; template <class Epi, class Sched>
; __device__ __forceinline__ void gemm_phase(LAS unsigned char* lds, const Gemm g, const Sched& S, const Epi& E) {
;     ...
;             PG8_LDA(At, 1, 1); PG8_STAGE(PG8_SA(1, 0), a3, voffA);
;             PG8_BAR; PG8_WAIT_L(0); PG8_MMA(1, 0, At, B0); PG8_BAR; PG8_SCHED;
;             PG8_STAGE(PG8_SB(1, 1), b3 + hstep, voffB);
;             PG8_WAIT_V(6); PG8_BAR; PG8_MMA(1, 1, At, B1); PG8_BAR;
;         }
	v_mfma_f32_16x16x32_bf16 v[66:69], v[238:241], v[222:225], v[66:69]
	s_setprio 0
	s_add_i32 m0, s99, 0xffffff80
	ds_read_b128 v[194:197], v166 offset:49152
	ds_read_b128 v[198:201], v166 offset:50176
	ds_read_b128 v[202:205], v166 offset:51200
	ds_read_b128 v[206:209], v166 offset:52224
	ds_read_b128 v[210:213], v166 offset:53248
	ds_read_b128 v[214:217], v166 offset:54272
	ds_read_b128 v[218:221], v166 offset:55296
	ds_read_b128 v[222:225], v166 offset:56320
	global_load_lds_dwordx4 v136, vcc offset:128
	s_add_i32 m0, s82, 0xffffff80
	s_nop 0
	global_load_lds_dwordx4 v132, vcc offset:128
	s_waitcnt vmcnt(8)
	s_barrier
	s_waitcnt lgkmcnt(0)
	s_setprio 1
	s_waitcnt lgkmcnt(0)
	v_mfma_f32_16x16x32_bf16 v[62:65], v[142:145], v[194:197], v[62:65]
	v_mfma_f32_16x16x32_bf16 v[62:65], v[182:185], v[198:201], v[62:65]
	v_mfma_f32_16x16x32_bf16 v[58:61], v[186:189], v[194:197], v[58:61]
	v_mfma_f32_16x16x32_bf16 v[58:61], v[190:193], v[198:201], v[58:61]
	v_mfma_f32_16x16x32_bf16 v[46:49], v[142:145], v[202:205], v[46:49]
	v_mfma_f32_16x16x32_bf16 v[46:49], v[182:185], v[206:209], v[46:49]
	v_mfma_f32_16x16x32_bf16 v[42:45], v[186:189], v[202:205], v[42:45]
	v_mfma_f32_16x16x32_bf16 v[42:45], v[190:193], v[206:209], v[42:45]
	v_mfma_f32_16x16x32_bf16 v[30:33], v[142:145], v[210:213], v[30:33]
	v_mfma_f32_16x16x32_bf16 v[30:33], v[182:185], v[214:217], v[30:33]
	v_mfma_f32_16x16x32_bf16 v[26:29], v[186:189], v[210:213], v[26:29]
	v_mfma_f32_16x16x32_bf16 v[26:29], v[190:193], v[214:217], v[26:29]
	v_mfma_f32_16x16x32_bf16 v[14:17], v[142:145], v[218:221], v[14:17]
	v_mfma_f32_16x16x32_bf16 v[14:17], v[182:185], v[222:225], v[14:17]
	v_mfma_f32_16x16x32_bf16 v[10:13], v[186:189], v[218:221], v[10:13]
	s_barrier
	v_mfma_f32_16x16x32_bf16 v[10:13], v[190:193], v[222:225], v[10:13]
	s_setprio 0
	s_add_u32 s24, s48, 0x40080
	s_addc_u32 s25, s49, 0
	s_add_i32 s39, s51, s94
	s_mov_b32 m0, s39
	s_nop 0
	global_load_lds_dwordx4 v134, s[24:25]
	s_add_i32 m0, s39, 0x2000
	s_nop 0
	global_load_lds_dwordx4 v130, s[24:25]
	s_waitcnt vmcnt(6)
	s_barrier
	s_setprio 1
	v_mfma_f32_16x16x32_bf16 v[54:57], v[226:229], v[194:197], v[54:57]
	ds_read_b128 v[142:145], v249
	ds_read_b128 v[182:185], v249 offset:1024
	v_mfma_f32_16x16x32_bf16 v[54:57], v[230:233], v[198:201], v[54:57]
	ds_read_b128 v[186:189], v249 offset:2048
	ds_read_b128 v[190:193], v249 offset:3072
	v_mfma_f32_16x16x32_bf16 v[50:53], v[234:237], v[194:197], v[50:53]
	ds_read_b128 v[194:197], v166
	v_mfma_f32_16x16x32_bf16 v[50:53], v[238:241], v[198:201], v[50:53]
	ds_read_b128 v[198:201], v166 offset:1024
	v_mfma_f32_16x16x32_bf16 v[38:41], v[226:229], v[202:205], v[38:41]
	v_mfma_f32_16x16x32_bf16 v[38:41], v[230:233], v[206:209], v[38:41]
	v_mfma_f32_16x16x32_bf16 v[34:37], v[234:237], v[202:205], v[34:37]
	ds_read_b128 v[202:205], v166 offset:2048
	v_mfma_f32_16x16x32_bf16 v[34:37], v[238:241], v[206:209], v[34:37]
	ds_read_b128 v[206:209], v166 offset:3072
	v_mfma_f32_16x16x32_bf16 v[22:25], v[226:229], v[210:213], v[22:25]
	v_mfma_f32_16x16x32_bf16 v[22:25], v[230:233], v[214:217], v[22:25]
	v_mfma_f32_16x16x32_bf16 v[18:21], v[234:237], v[210:213], v[18:21]
	ds_read_b128 v[210:213], v166 offset:4096
	v_mfma_f32_16x16x32_bf16 v[18:21], v[238:241], v[214:217], v[18:21]
	ds_read_b128 v[214:217], v166 offset:5120
	v_mfma_f32_16x16x32_bf16 v[6:9], v[226:229], v[218:221], v[6:9]
	v_mfma_f32_16x16x32_bf16 v[6:9], v[230:233], v[222:225], v[6:9]
	v_mfma_f32_16x16x32_bf16 v[2:5], v[234:237], v[218:221], v[2:5]
	s_barrier
	v_mfma_f32_16x16x32_bf16 v[2:5], v[238:241], v[222:225], v[2:5]
	s_setprio 0
	s_add_i32 s38, s38, 2
	s_add_u32 s35, s35, 0x100
	s_addc_u32 s50, s50, 0
	s_add_u32 s0, s0, 0x100
	s_addc_u32 s1, s1, 0
	s_cmp_gt_u32 s38, 13
	s_cbranch_scc0 .LBB0_557
	s_waitcnt lgkmcnt(0)
	s_and_b64 vcc, exec, s[42:43]
	s_cbranch_vccz .LBB0_560
	s_barrier

; #define PG8_STAGE(bufoff, gbase, voff) do { _Pragma("unroll") for (int _i = 0; _i < 2; ++_i) \
;         __builtin_amdgcn_global_load_lds((const unsigned*)((const char*)(gbase) + (voff)[_i]), (LAS unsigned*)(lds + (bufoff) + ldsw + _i * 8192), 16, 0, 0); } while (0)
; #define PG8_LDA(dst, b, h) do { _Pragma("unroll") for (int m = 0; m < 4; ++m) _Pragma("unroll") for (int k = 0; k < 2; ++k) dst[m][k] = *(const LAS bf16x8*)(lds + PG8_SA(b, h) + aoff + m * 2048 + k * 1024); } while (0)
; #define PG8_LDB(dst, b, h) do { _Pragma("unroll") for (int n = 0; n < 2; ++n) _Pragma("unroll") for (int k = 0; k < 2; ++k) dst[n][k] = *(const LAS bf16x8*)(lds + PG8_SB(b, h) + boff + n * 2048 + k * 1024); } while (0)
; #define PG8_MMA(ai, bj, At, Bt) do { __builtin_amdgcn_s_setprio(1); _Pragma("unroll") for (int m = 0; m < 4; ++m) _Pragma("unroll") for (int n = 0; n < 2; ++n) _Pragma("unroll") for (int k = 0; k < 2; ++k) \
;         acc[ai][bj][m][n] = __builtin_amdgcn_mfma_f32_16x16x32_bf16(Bt[n][k], At[m][k], acc[ai][bj][m][n], 0, 0, 0); __builtin_amdgcn_s_setprio(0); } while (0)
; #define PG8_WAIT_V(n) asm volatile("s_waitcnt vmcnt(" #n ")" ::: "memory")
; #define PG8_WAIT_L(n) asm volatile("s_waitcnt lgkmcnt(" #n ")" ::: "memory")
; #define PG8_BAR __builtin_amdgcn_s_barrier()
; template <class Epi, class Sched>
; __device__ __forceinline__ void gemm_phase(LAS unsigned char* lds, const Gemm g, const Sched& S, const Epi& E) {
;     ...
;             const bool last = (t == nt - 2);
;             const char* a1 = cA + (size_t)(t + 1) * kstep;
;             const char* a2 = last ? nA : cA + (size_t)(t + 2) * kstep; const char* b2 = last ? nB : cB + (size_t)(t + 2) * kstep;
;             const char* a3 = a2 + kstep; const char* b3 = b2 + kstep;
;             PG8_LDB(B0, 0, 0); PG8_SCHED; PG8_LDA(At, 0, 0); PG8_STAGE(PG8_SA(1, 1), a1 + hstep, voffA);
;             PG8_WAIT_L(8); PG8_BAR; PG8_WAIT_L(0); PG8_MMA(0, 0, At, B0); PG8_BAR; PG8_SCHED;
;             PG8_LDB(B1, 0, 1); PG8_STAGE(PG8_SB(0, 0), b2, voffB);
;             PG8_BAR; PG8_WAIT_L(0); PG8_MMA(0, 1, At, B1); PG8_BAR;
;             PG8_LDA(At, 0, 1); PG8_STAGE(PG8_SA(0, 0), a2, voffA);
;             PG8_BAR; PG8_WAIT_L(0); PG8_MMA(1, 0, At, B0); PG8_BAR; PG8_SCHED;
;             PG8_STAGE(PG8_SB(0, 1), b2 + hstep, voffB);
;             PG8_WAIT_V(6); PG8_BAR; PG8_MMA(1, 1, At, B1); PG8_BAR;
.LBB0_627:
	s_add_u32 s24, s0, 0xfff00080
	s_addc_u32 s25, s1, -1
	s_add_i32 s51, 0, 0x10000
	s_cmp_eq_u32 s98, 60
	s_cselect_b32 s77, s47, s25
	s_cselect_b32 s76, s46, s24
	s_cselect_b32 s49, s43, s50
	s_cselect_b32 s48, s45, s35
	s_add_i32 m0, s86, 0xc000
	ds_read_b128 v[218:221], v162 offset:6144
	ds_read_b128 v[222:225], v162 offset:7168
	global_load_lds_dwordx4 v140, s[0:1]
	s_add_i32 m0, s86, 0xe000
	s_nop 0
	global_load_lds_dwordx4 v138, s[0:1]
	s_waitcnt lgkmcnt(8)
	s_barrier
	s_waitcnt lgkmcnt(0)
	s_setprio 1
	s_waitcnt lgkmcnt(0)
	v_mfma_f32_16x16x32_bf16 v[126:129], v[164:167], v[194:197], v[126:129]
	v_mfma_f32_16x16x32_bf16 v[126:129], v[182:185], v[198:201], v[126:129]
	v_mfma_f32_16x16x32_bf16 v[122:125], v[186:189], v[194:197], v[122:125]
	v_mfma_f32_16x16x32_bf16 v[122:125], v[190:193], v[198:201], v[122:125]
	v_mfma_f32_16x16x32_bf16 v[118:121], v[164:167], v[202:205], v[118:121]
	v_mfma_f32_16x16x32_bf16 v[118:121], v[182:185], v[206:209], v[118:121]
	v_mfma_f32_16x16x32_bf16 v[110:113], v[186:189], v[202:205], v[110:113]
	v_mfma_f32_16x16x32_bf16 v[110:113], v[190:193], v[206:209], v[110:113]
	v_mfma_f32_16x16x32_bf16 v[102:105], v[164:167], v[210:213], v[102:105]
	v_mfma_f32_16x16x32_bf16 v[102:105], v[182:185], v[214:217], v[102:105]
	v_mfma_f32_16x16x32_bf16 v[94:97], v[186:189], v[210:213], v[94:97]
	v_mfma_f32_16x16x32_bf16 v[94:97], v[190:193], v[214:217], v[94:97]
	v_mfma_f32_16x16x32_bf16 v[86:89], v[164:167], v[218:221], v[86:89]
	v_mfma_f32_16x16x32_bf16 v[86:89], v[182:185], v[222:225], v[86:89]
	v_mfma_f32_16x16x32_bf16 v[78:81], v[186:189], v[218:221], v[78:81]
	s_barrier
	v_mfma_f32_16x16x32_bf16 v[78:81], v[190:193], v[222:225], v[78:81]
	s_setprio 0
	s_add_i32 s99, 0, 0x14000
	s_add_i32 s24, s51, s83
	ds_read_b128 v[226:229], v249 offset:16384
	ds_read_b128 v[230:233], v249 offset:17408
	ds_read_b128 v[234:237], v249 offset:18432
	ds_read_b128 v[238:241], v249 offset:19456
	s_mov_b32 m0, s24
	global_load_lds_dwordx4 v134, s[48:49]
	s_add_i32 m0, s24, 0x2000
	s_nop 0
	global_load_lds_dwordx4 v130, s[48:49]
	s_barrier
	s_waitcnt lgkmcnt(0)
	s_setprio 1
	s_waitcnt lgkmcnt(0)
	v_mfma_f32_16x16x32_bf16 v[114:117], v[226:229], v[194:197], v[114:117]
	v_mfma_f32_16x16x32_bf16 v[114:117], v[230:233], v[198:201], v[114:117]
	v_mfma_f32_16x16x32_bf16 v[106:109], v[234:237], v[194:197], v[106:109]
	v_mfma_f32_16x16x32_bf16 v[106:109], v[238:241], v[198:201], v[106:109]
	v_mfma_f32_16x16x32_bf16 v[98:101], v[226:229], v[202:205], v[98:101]
	v_mfma_f32_16x16x32_bf16 v[98:101], v[230:233], v[206:209], v[98:101]
	v_mfma_f32_16x16x32_bf16 v[90:93], v[234:237], v[202:205], v[90:93]
	v_mfma_f32_16x16x32_bf16 v[90:93], v[238:241], v[206:209], v[90:93]
	v_mfma_f32_16x16x32_bf16 v[82:85], v[226:229], v[210:213], v[82:85]
	v_mfma_f32_16x16x32_bf16 v[82:85], v[230:233], v[214:217], v[82:85]
	v_mfma_f32_16x16x32_bf16 v[74:77], v[234:237], v[210:213], v[74:77]
	v_mfma_f32_16x16x32_bf16 v[74:77], v[238:241], v[214:217], v[74:77]
	v_mfma_f32_16x16x32_bf16 v[70:73], v[226:229], v[218:221], v[70:73]
	v_mfma_f32_16x16x32_bf16 v[70:73], v[230:233], v[222:225], v[70:73]
	v_mfma_f32_16x16x32_bf16 v[66:69], v[234:237], v[218:221], v[66:69]
	s_barrier
	v_mfma_f32_16x16x32_bf16 v[66:69], v[238:241], v[222:225], v[66:69]
	s_setprio 0
	s_mov_b32 m0, s86
	s_mov_b64 s[100:101], s[76:77]
	ds_read_b128 v[194:197], v162 offset:16384
	ds_read_b128 v[198:201], v162 offset:17408
	ds_read_b128 v[202:205], v162 offset:18432
	ds_read_b128 v[206:209], v162 offset:19456
	ds_read_b128 v[210:213], v162 offset:20480
	ds_read_b128 v[214:217], v162 offset:21504
	ds_read_b128 v[218:221], v162 offset:22528
	ds_read_b128 v[222:225], v162 offset:23552
	global_load_lds_dwordx4 v136, s[76:77]
	s_mov_b64 s[100:101], s[76:77]
	s_mov_b32 m0, s92
	s_nop 0
	global_load_lds_dwordx4 v132, s[76:77]
	s_waitcnt vmcnt(8)
	s_barrier
	s_waitcnt lgkmcnt(0)
	s_setprio 1
	s_waitcnt lgkmcnt(0)
	v_mfma_f32_16x16x32_bf16 v[62:65], v[164:167], v[194:197], v[62:65]
	v_mfma_f32_16x16x32_bf16 v[62:65], v[182:185], v[198:201], v[62:65]
	v_mfma_f32_16x16x32_bf16 v[58:61], v[186:189], v[194:197], v[58:61]
	v_mfma_f32_16x16x32_bf16 v[58:61], v[190:193], v[198:201], v[58:61]
	v_mfma_f32_16x16x32_bf16 v[54:57], v[164:167], v[202:205], v[54:57]
	v_mfma_f32_16x16x32_bf16 v[54:57], v[182:185], v[206:209], v[54:57]
	v_mfma_f32_16x16x32_bf16 v[46:49], v[186:189], v[202:205], v[46:49]
	v_mfma_f32_16x16x32_bf16 v[46:49], v[190:193], v[206:209], v[46:49]
	v_mfma_f32_16x16x32_bf16 v[38:41], v[164:167], v[210:213], v[38:41]
	v_mfma_f32_16x16x32_bf16 v[38:41], v[182:185], v[214:217], v[38:41]
	v_mfma_f32_16x16x32_bf16 v[30:33], v[186:189], v[210:213], v[30:33]
	v_mfma_f32_16x16x32_bf16 v[30:33], v[190:193], v[214:217], v[30:33]
	v_mfma_f32_16x16x32_bf16 v[22:25], v[164:167], v[218:221], v[22:25]
	v_mfma_f32_16x16x32_bf16 v[22:25], v[182:185], v[222:225], v[22:25]
	v_mfma_f32_16x16x32_bf16 v[14:17], v[186:189], v[218:221], v[14:17]
	s_barrier
	v_mfma_f32_16x16x32_bf16 v[14:17], v[190:193], v[222:225], v[14:17]
	s_setprio 0
	s_add_u32 s24, s48, 0x100000
	s_addc_u32 s25, s49, 0
	s_add_i32 s51, s99, s83
	s_mov_b32 m0, s51
	s_nop 0
	global_load_lds_dwordx4 v134, s[24:25]
	s_add_i32 m0, s51, 0x2000
	s_nop 0
	global_load_lds_dwordx4 v130, s[24:25]
	s_waitcnt vmcnt(6)
	s_barrier
; #define PG8_STAGE(bufoff, gbase, voff) do { _Pragma("unroll") for (int _i = 0; _i < 2; ++_i) \
;         __builtin_amdgcn_global_load_lds((const unsigned*)((const char*)(gbase) + (voff)[_i]), (LAS unsigned*)(lds + (bufoff) + ldsw + _i * 8192), 16, 0, 0); } while (0)
; #define PG8_LDA(dst, b, h) do { _Pragma("unroll") for (int m = 0; m < 4; ++m) _Pragma("unroll") for (int k = 0; k < 2; ++k) dst[m][k] = *(const LAS bf16x8*)(lds + PG8_SA(b, h) + aoff + m * 2048 + k * 1024); } while (0)
; #define PG8_LDB(dst, b, h) do { _Pragma("unroll") for (int n = 0; n < 2; ++n) _Pragma("unroll") for (int k = 0; k < 2; ++k) dst[n][k] = *(const LAS bf16x8*)(lds + PG8_SB(b, h) + boff + n * 2048 + k * 1024); } while (0)
; #define PG8_MMA(ai, bj, At, Bt) do { __builtin_amdgcn_s_setprio(1); _Pragma("unroll") for (int m = 0; m < 4; ++m) _Pragma("unroll") for (int n = 0; n < 2; ++n) _Pragma("unroll") for (int k = 0; k < 2; ++k) \
;         acc[ai][bj][m][n] = __builtin_amdgcn_mfma_f32_16x16x32_bf16(Bt[n][k], At[m][k], acc[ai][bj][m][n], 0, 0, 0); __builtin_amdgcn_s_setprio(0); } while (0)
; #define PG8_WAIT_V(n) asm volatile("s_waitcnt vmcnt(" #n ")" ::: "memory")
; #define PG8_WAIT_L(n) asm volatile("s_waitcnt lgkmcnt(" #n ")" ::: "memory")
; #define PG8_BAR __builtin_amdgcn_s_barrier()
; #define PG8_SCHED __builtin_amdgcn_sched_barrier(0)
; template <class Epi, class Sched>
; __device__ __forceinline__ void gemm_phase(LAS unsigned char* lds, const Gemm g, const Sched& S, const Epi& E) {
;     ...
;             PG8_WAIT_V(6); PG8_BAR; PG8_MMA(1, 1, At, B1); PG8_BAR;
;             PG8_LDB(B0, 1, 0); PG8_SCHED; PG8_LDA(At, 1, 0); PG8_STAGE(PG8_SA(0, 1), a2 + hstep, voffA);
;             PG8_WAIT_L(8); PG8_BAR; PG8_WAIT_L(0); PG8_MMA(0, 0, At, B0); PG8_BAR; PG8_SCHED;
;             PG8_LDB(B1, 1, 1); PG8_STAGE(PG8_SB(1, 0), b3, voffB);
;             PG8_BAR; PG8_WAIT_L(0); PG8_MMA(0, 1, At, B1); PG8_BAR;
;             PG8_LDA(At, 1, 1); PG8_STAGE(PG8_SA(1, 0), a3, voffA);
	s_setprio 1
	v_mfma_f32_16x16x32_bf16 v[50:53], v[226:229], v[194:197], v[50:53]
	ds_read_b128 v[164:167], v249 offset:32768
	ds_read_b128 v[182:185], v249 offset:33792
	v_mfma_f32_16x16x32_bf16 v[50:53], v[230:233], v[198:201], v[50:53]
	ds_read_b128 v[186:189], v249 offset:34816
	ds_read_b128 v[190:193], v249 offset:35840
	v_mfma_f32_16x16x32_bf16 v[42:45], v[234:237], v[194:197], v[42:45]
	ds_read_b128 v[194:197], v162 offset:32768
	v_mfma_f32_16x16x32_bf16 v[42:45], v[238:241], v[198:201], v[42:45]
	ds_read_b128 v[198:201], v162 offset:33792
	v_mfma_f32_16x16x32_bf16 v[34:37], v[226:229], v[202:205], v[34:37]
	v_mfma_f32_16x16x32_bf16 v[34:37], v[230:233], v[206:209], v[34:37]
	v_mfma_f32_16x16x32_bf16 v[26:29], v[234:237], v[202:205], v[26:29]
	ds_read_b128 v[202:205], v162 offset:34816
	v_mfma_f32_16x16x32_bf16 v[26:29], v[238:241], v[206:209], v[26:29]
	ds_read_b128 v[206:209], v162 offset:35840
	v_mfma_f32_16x16x32_bf16 v[18:21], v[226:229], v[210:213], v[18:21]
	v_mfma_f32_16x16x32_bf16 v[18:21], v[230:233], v[214:217], v[18:21]
	v_mfma_f32_16x16x32_bf16 v[10:13], v[234:237], v[210:213], v[10:13]
	ds_read_b128 v[210:213], v162 offset:36864
	v_mfma_f32_16x16x32_bf16 v[10:13], v[238:241], v[214:217], v[10:13]
	ds_read_b128 v[214:217], v162 offset:37888
	v_mfma_f32_16x16x32_bf16 v[6:9], v[226:229], v[218:221], v[6:9]
	v_mfma_f32_16x16x32_bf16 v[6:9], v[230:233], v[222:225], v[6:9]
	v_mfma_f32_16x16x32_bf16 v[2:5], v[234:237], v[218:221], v[2:5]
	s_barrier
	v_mfma_f32_16x16x32_bf16 v[2:5], v[238:241], v[222:225], v[2:5]
	s_setprio 0
	s_add_i32 s51, 0, 0x18000
	s_add_u32 s24, s76, 0x100000
	s_addc_u32 s25, s77, 0
	s_mov_b32 m0, s93
	ds_read_b128 v[218:221], v162 offset:38912
	ds_read_b128 v[222:225], v162 offset:39936
	global_load_lds_dwordx4 v136, s[24:25]
	s_mov_b32 m0, s94
	s_nop 0
	global_load_lds_dwordx4 v132, s[24:25]
	s_waitcnt lgkmcnt(8)
	s_barrier
	s_waitcnt lgkmcnt(0)
	s_setprio 1
	s_waitcnt lgkmcnt(0)
	v_mfma_f32_16x16x32_bf16 v[126:129], v[164:167], v[194:197], v[126:129]
	v_mfma_f32_16x16x32_bf16 v[126:129], v[182:185], v[198:201], v[126:129]
	v_mfma_f32_16x16x32_bf16 v[122:125], v[186:189], v[194:197], v[122:125]
	v_mfma_f32_16x16x32_bf16 v[122:125], v[190:193], v[198:201], v[122:125]
	v_mfma_f32_16x16x32_bf16 v[118:121], v[164:167], v[202:205], v[118:121]
	v_mfma_f32_16x16x32_bf16 v[118:121], v[182:185], v[206:209], v[118:121]
	v_mfma_f32_16x16x32_bf16 v[110:113], v[186:189], v[202:205], v[110:113]
	v_mfma_f32_16x16x32_bf16 v[110:113], v[190:193], v[206:209], v[110:113]
	v_mfma_f32_16x16x32_bf16 v[102:105], v[164:167], v[210:213], v[102:105]
	v_mfma_f32_16x16x32_bf16 v[102:105], v[182:185], v[214:217], v[102:105]
	v_mfma_f32_16x16x32_bf16 v[94:97], v[186:189], v[210:213], v[94:97]
	v_mfma_f32_16x16x32_bf16 v[94:97], v[190:193], v[214:217], v[94:97]
	v_mfma_f32_16x16x32_bf16 v[86:89], v[164:167], v[218:221], v[86:89]
	v_mfma_f32_16x16x32_bf16 v[86:89], v[182:185], v[222:225], v[86:89]
	v_mfma_f32_16x16x32_bf16 v[78:81], v[186:189], v[218:221], v[78:81]
	s_barrier
	v_mfma_f32_16x16x32_bf16 v[78:81], v[190:193], v[222:225], v[78:81]
	s_setprio 0
	s_add_i32 s76, 0, 0x1c000
	s_add_i32 s24, s51, s83
	s_add_i32 m0, s24, 0xffffff80
	ds_read_b128 v[226:229], v249 offset:49152
	ds_read_b128 v[230:233], v249 offset:50176
	ds_read_b128 v[234:237], v249 offset:51200
	ds_read_b128 v[238:241], v249 offset:52224
	global_load_lds_dwordx4 v134, s[48:49] offset:128
	s_add_i32 m0, s24, 0x1f80
	s_nop 0
	global_load_lds_dwordx4 v130, s[48:49] offset:128
	s_barrier
	s_waitcnt lgkmcnt(0)
	s_setprio 1
	s_waitcnt lgkmcnt(0)
	v_mfma_f32_16x16x32_bf16 v[114:117], v[226:229], v[194:197], v[114:117]
	v_mfma_f32_16x16x32_bf16 v[114:117], v[230:233], v[198:201], v[114:117]
	v_mfma_f32_16x16x32_bf16 v[106:109], v[234:237], v[194:197], v[106:109]
	v_mfma_f32_16x16x32_bf16 v[106:109], v[238:241], v[198:201], v[106:109]
	v_mfma_f32_16x16x32_bf16 v[98:101], v[226:229], v[202:205], v[98:101]
	v_mfma_f32_16x16x32_bf16 v[98:101], v[230:233], v[206:209], v[98:101]
	v_mfma_f32_16x16x32_bf16 v[90:93], v[234:237], v[202:205], v[90:93]
	v_mfma_f32_16x16x32_bf16 v[90:93], v[238:241], v[206:209], v[90:93]
	v_mfma_f32_16x16x32_bf16 v[82:85], v[226:229], v[210:213], v[82:85]
	v_mfma_f32_16x16x32_bf16 v[82:85], v[230:233], v[214:217], v[82:85]
	v_mfma_f32_16x16x32_bf16 v[74:77], v[234:237], v[210:213], v[74:77]
	v_mfma_f32_16x16x32_bf16 v[74:77], v[238:241], v[214:217], v[74:77]
	v_mfma_f32_16x16x32_bf16 v[70:73], v[226:229], v[218:221], v[70:73]
	v_mfma_f32_16x16x32_bf16 v[70:73], v[230:233], v[222:225], v[70:73]
	v_mfma_f32_16x16x32_bf16 v[66:69], v[234:237], v[218:221], v[66:69]
	s_barrier
; #define PG8_STAGE(bufoff, gbase, voff) do { _Pragma("unroll") for (int _i = 0; _i < 2; ++_i) \
;         __builtin_amdgcn_global_load_lds((const unsigned*)((const char*)(gbase) + (voff)[_i]), (LAS unsigned*)(lds + (bufoff) + ldsw + _i * 8192), 16, 0, 0); } while (0)
; #define PG8_LDA(dst, b, h) do { _Pragma("unroll") for (int m = 0; m < 4; ++m) _Pragma("unroll") for (int k = 0; k < 2; ++k) dst[m][k] = *(const LAS bf16x8*)(lds + PG8_SA(b, h) + aoff + m * 2048 + k * 1024); } while (0)
; #define PG8_MMA(ai, bj, At, Bt) do { __builtin_amdgcn_s_setprio(1); _Pragma("unroll") for (int m = 0; m < 4; ++m) _Pragma("unroll") for (int n = 0; n < 2; ++n) _Pragma("unroll") for (int k = 0; k < 2; ++k) \
;         acc[ai][bj][m][n] = __builtin_amdgcn_mfma_f32_16x16x32_bf16(Bt[n][k], At[m][k], acc[ai][bj][m][n], 0, 0, 0); __builtin_amdgcn_s_setprio(0); } while (0)
; #define PG8_WAIT_V(n) asm volatile("s_waitcnt vmcnt(" #n ")" ::: "memory")
; #define PG8_WAIT_L(n) asm volatile("s_waitcnt lgkmcnt(" #n ")" ::: "memory")
; #define PG8_BAR __builtin_amdgcn_s_barrier()
; #define PG8_SCHED __builtin_amdgcn_sched_barrier(0)
; template <class Epi, class Sched>
; __device__ __forceinline__ void gemm_phase(LAS unsigned char* lds, const Gemm g, const Sched& S, const Epi& E) {
;     ...
;             PG8_LDA(At, 1, 1); PG8_STAGE(PG8_SA(1, 0), a3, voffA);
;             PG8_BAR; PG8_WAIT_L(0); PG8_MMA(1, 0, At, B0); PG8_BAR; PG8_SCHED;
;             PG8_STAGE(PG8_SB(1, 1), b3 + hstep, voffB);
;             PG8_WAIT_V(6); PG8_BAR; PG8_MMA(1, 1, At, B1); PG8_BAR;
;         }
	v_mfma_f32_16x16x32_bf16 v[66:69], v[238:241], v[222:225], v[66:69]
	s_setprio 0
	s_add_i32 m0, s95, 0xffffff80
	ds_read_b128 v[194:197], v162 offset:49152
	ds_read_b128 v[198:201], v162 offset:50176
	ds_read_b128 v[202:205], v162 offset:51200
	ds_read_b128 v[206:209], v162 offset:52224
	ds_read_b128 v[210:213], v162 offset:53248
	ds_read_b128 v[214:217], v162 offset:54272
	ds_read_b128 v[218:221], v162 offset:55296
	ds_read_b128 v[222:225], v162 offset:56320
	global_load_lds_dwordx4 v136, s[100:101] offset:128
	s_add_i32 m0, s96, 0xffffff80
	s_nop 0
	global_load_lds_dwordx4 v132, s[100:101] offset:128
	s_waitcnt vmcnt(8)
	s_barrier
	s_waitcnt lgkmcnt(0)
	s_setprio 1
	s_waitcnt lgkmcnt(0)
	v_mfma_f32_16x16x32_bf16 v[62:65], v[164:167], v[194:197], v[62:65]
	v_mfma_f32_16x16x32_bf16 v[62:65], v[182:185], v[198:201], v[62:65]
	v_mfma_f32_16x16x32_bf16 v[58:61], v[186:189], v[194:197], v[58:61]
	v_mfma_f32_16x16x32_bf16 v[58:61], v[190:193], v[198:201], v[58:61]
	v_mfma_f32_16x16x32_bf16 v[54:57], v[164:167], v[202:205], v[54:57]
	v_mfma_f32_16x16x32_bf16 v[54:57], v[182:185], v[206:209], v[54:57]
	v_mfma_f32_16x16x32_bf16 v[46:49], v[186:189], v[202:205], v[46:49]
	v_mfma_f32_16x16x32_bf16 v[46:49], v[190:193], v[206:209], v[46:49]
	v_mfma_f32_16x16x32_bf16 v[38:41], v[164:167], v[210:213], v[38:41]
	v_mfma_f32_16x16x32_bf16 v[38:41], v[182:185], v[214:217], v[38:41]
	v_mfma_f32_16x16x32_bf16 v[30:33], v[186:189], v[210:213], v[30:33]
	v_mfma_f32_16x16x32_bf16 v[30:33], v[190:193], v[214:217], v[30:33]
	v_mfma_f32_16x16x32_bf16 v[22:25], v[164:167], v[218:221], v[22:25]
	v_mfma_f32_16x16x32_bf16 v[22:25], v[182:185], v[222:225], v[22:25]
	v_mfma_f32_16x16x32_bf16 v[14:17], v[186:189], v[218:221], v[14:17]
	s_barrier
	v_mfma_f32_16x16x32_bf16 v[14:17], v[190:193], v[222:225], v[14:17]
	s_setprio 0
	s_add_u32 s24, s48, 0x100080
	s_addc_u32 s25, s49, 0
	s_add_i32 s48, s76, s83
	s_mov_b32 m0, s48
	s_nop 0
	global_load_lds_dwordx4 v134, s[24:25]
	s_add_i32 m0, s48, 0x2000
	s_nop 0
	global_load_lds_dwordx4 v130, s[24:25]
	s_waitcnt vmcnt(6)
	s_barrier
	s_setprio 1
	v_mfma_f32_16x16x32_bf16 v[50:53], v[226:229], v[194:197], v[50:53]
	ds_read_b128 v[164:167], v249
	ds_read_b128 v[182:185], v249 offset:1024
	v_mfma_f32_16x16x32_bf16 v[50:53], v[230:233], v[198:201], v[50:53]
	ds_read_b128 v[186:189], v249 offset:2048
	ds_read_b128 v[190:193], v249 offset:3072
	v_mfma_f32_16x16x32_bf16 v[42:45], v[234:237], v[194:197], v[42:45]
	ds_read_b128 v[194:197], v162
	v_mfma_f32_16x16x32_bf16 v[42:45], v[238:241], v[198:201], v[42:45]
	ds_read_b128 v[198:201], v162 offset:1024
	v_mfma_f32_16x16x32_bf16 v[34:37], v[226:229], v[202:205], v[34:37]
	v_mfma_f32_16x16x32_bf16 v[34:37], v[230:233], v[206:209], v[34:37]
	v_mfma_f32_16x16x32_bf16 v[26:29], v[234:237], v[202:205], v[26:29]
	ds_read_b128 v[202:205], v162 offset:2048
	v_mfma_f32_16x16x32_bf16 v[26:29], v[238:241], v[206:209], v[26:29]
	ds_read_b128 v[206:209], v162 offset:3072
	v_mfma_f32_16x16x32_bf16 v[18:21], v[226:229], v[210:213], v[18:21]
	v_mfma_f32_16x16x32_bf16 v[18:21], v[230:233], v[214:217], v[18:21]
	v_mfma_f32_16x16x32_bf16 v[10:13], v[234:237], v[210:213], v[10:13]
	ds_read_b128 v[210:213], v162 offset:4096
	v_mfma_f32_16x16x32_bf16 v[10:13], v[238:241], v[214:217], v[10:13]
	ds_read_b128 v[214:217], v162 offset:5120
	v_mfma_f32_16x16x32_bf16 v[6:9], v[226:229], v[218:221], v[6:9]
	v_mfma_f32_16x16x32_bf16 v[6:9], v[230:233], v[222:225], v[6:9]
	v_mfma_f32_16x16x32_bf16 v[2:5], v[234:237], v[218:221], v[2:5]
	s_barrier
	v_mfma_f32_16x16x32_bf16 v[2:5], v[238:241], v[222:225], v[2:5]
	s_setprio 0
	s_add_i32 s98, s98, 2
	s_add_u32 s35, s35, 0x100
	s_addc_u32 s50, s50, 0
	s_add_u32 s0, s0, 0x100
	s_addc_u32 s1, s1, 0
	s_cmp_gt_u32 s98, 61
	s_cbranch_scc0 .LBB0_627
	s_waitcnt lgkmcnt(0)
	s_and_b64 vcc, exec, s[40:41]
	s_cbranch_vccz .LBB0_630
	s_barrier
